# GEMM K-loop first iteration peeled with zero SrcC: per-unit accumulator zeroing (128 moves per wave) removed
# speedup vs baseline: 1.0044x; 1.0044x over previous
; #define PG8_STAGE(bufoff, gbase, RR, ld) do { _Pragma("unroll") for (int _i = 0; _i < 2; ++_i) \
;         __builtin_amdgcn_global_load_lds((const unsigned*)((const char*)(gbase) + (RR)[_i] * (ld) + C2[_i]), (LAS unsigned*)(lds + (bufoff) + ldsw + _i * 8192), 16, 0, 0); } while (0)
; #define PG8_LDA(dst, b, h) do { _Pragma("unroll") for (int m = 0; m < 4; ++m) _Pragma("unroll") for (int k = 0; k < 2; ++k) dst[m][k] = *(const LAS bf16x8*)(lds + PG8_SA(b, h) + aoff + m * 2048 + k * 1024); } while (0)
; #define PG8_LDB(dst, b, h) do { _Pragma("unroll") for (int n = 0; n < 2; ++n) _Pragma("unroll") for (int k = 0; k < 2; ++k) dst[n][k] = *(const LAS bf16x8*)(lds + PG8_SB(b, h) + boff + n * 2048 + k * 1024); } while (0)
; #define PG8_WAIT_V(n) asm volatile("s_waitcnt vmcnt(" #n ")" ::: "memory")
; template <class Sched, class Epi>
; __device__ __forceinline__ void gemm_run(LAS unsigned char* lds, const Sched& S, const Epi& E) {
;     ...
;     f32x4 acc[2][2][4][2];
; #pragma unroll
;     for (int a = 0; a < 2; ++a)
; #pragma unroll
;         for (int b = 0; b < 2; ++b)
; #pragma unroll
;             for (int m = 0; m < 4; ++m)
; #pragma unroll
;                 for (int n = 0; n < 2; ++n) acc[a][b][m][n] = (f32x4){0.f, 0.f, 0.f, 0.f};
;     ...
;     for (;;) {
;         const bool has_next = S.next(ui + 1, nxt);
;         const char* nA = has_next ? nxt.A : cA; const char* nB = has_next ? nxt.B : cB; const unsigned nlda = has_next ? nxt.lda : lda, nldb = has_next ? nxt.ldb : ldb;
;         const int nt = cur.nt;
;         for (int t = 0; t < nt; t += 2) {
;             const bool last = (t == nt - 2);
;             const char* a1 = cA + (size_t)(t + 1) * kstep;
;             const char* a2 = last ? nA : cA + (size_t)(t + 2) * kstep; const char* b2 = last ? nB : cB + (size_t)(t + 2) * kstep;
;             const unsigned la2 = last ? nlda : lda, lb2 = last ? nldb : ldb;
;             const char* a3 = a2 + kstep; const char* b3 = b2 + kstep;
;             PG8_LDB(B0, 0, 0); PG8_LDB(B1, 0, 1); PG8_SCHED; PG8_LDA(At, 0, 0); PG8_STAGE(PG8_SA(1, 1), a1 + (size_t)HALF * lda, RA, lda);
;             PG8_WAIT_V(8); PG8_WAIT_L(0); PG8_BAR; PG8_MMA(0, 0, At, B0); PG8_MMA(0, 1, At, B1); PG8_BAR; PG8_SCHED;
;             PG8_LDA(At, 0, 1); PG8_STAGE(PG8_SB(0, 0), b2, RB, lb2); PG8_STAGE(PG8_SB(0, 1), b2 + (size_t)HALF * lb2, RB, lb2); PG8_STAGE(PG8_SA(0, 0), a2, RA, la2);
.LBB0_245:
	s_add_u32 s12, s54, 0x100
	s_addc_u32 s33, s55, 0
	s_mov_b32 s38, -2
	s_mov_b64 s[54:55], 0
	s_waitcnt lgkmcnt(0)
	v_lshl_add_u64 v[150:151], s[6:7], 0, v[146:147]
	s_waitcnt vmcnt(0)
	v_lshl_add_u64 v[152:153], s[6:7], 0, v[148:149]
	ds_read_b128 v[154:157], v182
	ds_read_b128 v[158:161], v182 offset:1024
	ds_read_b128 v[162:165], v182 offset:2048
	ds_read_b128 v[166:169], v182 offset:3072
	ds_read_b128 v[170:173], v183
	ds_read_b128 v[186:189], v183 offset:1024
	ds_read_b128 v[190:193], v183 offset:2048
	ds_read_b128 v[194:197], v183 offset:3072
	s_add_u32 s39, s6, s54
	s_addc_u32 s40, s7, s55
	s_add_u32 s39, s39, 0x100
	s_addc_u32 s40, s40, 0
	s_add_u32 s41, s12, s54
	s_addc_u32 s42, s33, s55
	s_cmpk_eq_i32 s54, 0xf00
	s_cselect_b32 s59, s29, s40
	s_cselect_b32 s58, s28, s39
	s_cselect_b32 s57, s37, s42
	s_cselect_b32 s56, s36, s41
	v_lshl_add_u64 v[174:175], v[150:151], 0, s[54:55]
	s_add_i32 m0, s21, 0xc000
	ds_read_b128 v[198:201], v184
	ds_read_b128 v[202:205], v184 offset:1024
	ds_read_b128 v[206:209], v184 offset:2048
	ds_read_b128 v[210:213], v184 offset:3072
	ds_read_b128 v[214:217], v184 offset:4096
	ds_read_b128 v[218:221], v184 offset:5120
	ds_read_b128 v[222:225], v184 offset:6144
	ds_read_b128 v[226:229], v184 offset:7168
	global_load_lds_dwordx4 v[174:175], off
	v_lshl_add_u64 v[174:175], v[152:153], 0, s[54:55]
	s_add_i32 m0, s21, 0xe000
	s_nop 0
	global_load_lds_dwordx4 v[174:175], off
	s_waitcnt vmcnt(8)
	s_waitcnt lgkmcnt(0)
	s_barrier
	s_waitcnt lgkmcnt(0)
	v_mfma_f32_16x16x32_bf16 v[126:129], v[154:157], v[198:201], 0
	v_mfma_f32_16x16x32_bf16 v[122:125], v[162:165], v[198:201], 0
	v_mfma_f32_16x16x32_bf16 v[110:113], v[154:157], v[206:209], 0
	v_mfma_f32_16x16x32_bf16 v[106:109], v[162:165], v[206:209], 0
	v_mfma_f32_16x16x32_bf16 v[94:97], v[154:157], v[214:217], 0
	v_mfma_f32_16x16x32_bf16 v[90:93], v[162:165], v[214:217], 0
	v_mfma_f32_16x16x32_bf16 v[78:81], v[154:157], v[222:225], 0
	v_mfma_f32_16x16x32_bf16 v[74:77], v[162:165], v[222:225], 0
	v_mfma_f32_16x16x32_bf16 v[126:129], v[158:161], v[202:205], v[126:129]
	v_mfma_f32_16x16x32_bf16 v[122:125], v[166:169], v[202:205], v[122:125]
	v_mfma_f32_16x16x32_bf16 v[110:113], v[158:161], v[210:213], v[110:113]
	v_mfma_f32_16x16x32_bf16 v[106:109], v[166:169], v[210:213], v[106:109]
	v_mfma_f32_16x16x32_bf16 v[94:97], v[158:161], v[218:221], v[94:97]
	v_mfma_f32_16x16x32_bf16 v[90:93], v[166:169], v[218:221], v[90:93]
	v_mfma_f32_16x16x32_bf16 v[78:81], v[158:161], v[226:229], v[78:81]
	v_mfma_f32_16x16x32_bf16 v[74:77], v[166:169], v[226:229], v[74:77]
	v_mfma_f32_16x16x32_bf16 v[118:121], v[170:173], v[198:201], 0
	v_mfma_f32_16x16x32_bf16 v[114:117], v[190:193], v[198:201], 0
	v_mfma_f32_16x16x32_bf16 v[102:105], v[170:173], v[206:209], 0
	v_mfma_f32_16x16x32_bf16 v[98:101], v[190:193], v[206:209], 0
	v_mfma_f32_16x16x32_bf16 v[86:89], v[170:173], v[214:217], 0
	v_mfma_f32_16x16x32_bf16 v[82:85], v[190:193], v[214:217], 0
	v_mfma_f32_16x16x32_bf16 v[70:73], v[170:173], v[222:225], 0
	v_mfma_f32_16x16x32_bf16 v[66:69], v[190:193], v[222:225], 0
	v_mfma_f32_16x16x32_bf16 v[118:121], v[186:189], v[202:205], v[118:121]
	v_mfma_f32_16x16x32_bf16 v[114:117], v[194:197], v[202:205], v[114:117]
	v_mfma_f32_16x16x32_bf16 v[102:105], v[186:189], v[210:213], v[102:105]
	v_mfma_f32_16x16x32_bf16 v[98:101], v[194:197], v[210:213], v[98:101]
	v_mfma_f32_16x16x32_bf16 v[86:89], v[186:189], v[218:221], v[86:89]
	v_mfma_f32_16x16x32_bf16 v[82:85], v[194:197], v[218:221], v[82:85]
	v_mfma_f32_16x16x32_bf16 v[70:73], v[186:189], v[226:229], v[70:73]
	v_mfma_f32_16x16x32_bf16 v[66:69], v[194:197], v[226:229], v[66:69]
	s_barrier
	v_lshl_add_u64 v[174:175], s[56:57], 0, v[132:133]
	s_add_i32 s39, s71, s3
	v_lshl_add_u64 v[174:175], v[174:175], 0, v[130:131]
	s_mov_b32 m0, s39
	ds_read_b128 v[198:201], v184 offset:16384
	ds_read_b128 v[202:205], v184 offset:17408
	ds_read_b128 v[206:209], v184 offset:18432
	ds_read_b128 v[210:213], v184 offset:19456
	ds_read_b128 v[214:217], v184 offset:20480
	ds_read_b128 v[218:221], v184 offset:21504
	ds_read_b128 v[222:225], v184 offset:22528
	ds_read_b128 v[226:229], v184 offset:23552
	global_load_lds_dwordx4 v[174:175], off
	s_add_i32 m0, s39, 0x2000
	s_add_u32 s40, s56, 0x80000
	v_lshl_add_u64 v[230:231], s[56:57], 0, v[136:137]
	s_addc_u32 s41, s57, 0
	v_lshl_add_u64 v[230:231], v[230:231], 0, v[130:131]
	v_lshl_add_u64 v[232:233], s[40:41], 0, v[132:133]
	s_add_i32 s39, s72, s3
	global_load_lds_dwordx4 v[230:231], off
	v_lshl_add_u64 v[232:233], v[232:233], 0, v[130:131]
	s_mov_b32 m0, s39
	v_lshl_add_u64 v[234:235], s[58:59], 0, v[140:141]
	global_load_lds_dwordx4 v[232:233], off
	v_lshl_add_u64 v[232:233], s[40:41], 0, v[136:137]
	v_lshl_add_u64 v[232:233], v[232:233], 0, v[130:131]
	s_add_i32 m0, s39, 0x2000
	v_lshl_add_u64 v[234:235], v[234:235], 0, v[130:131]
	global_load_lds_dwordx4 v[232:233], off
	v_lshl_add_u64 v[232:233], s[58:59], 0, v[138:139]
	v_lshl_add_u64 v[232:233], v[232:233], 0, v[130:131]
	s_mov_b32 m0, s21
	s_nop 0
	global_load_lds_dwordx4 v[232:233], off
	s_mov_b32 m0, s35
	s_nop 0
	global_load_lds_dwordx4 v[234:235], off
	s_waitcnt vmcnt(8)
	s_waitcnt lgkmcnt(0)
	s_barrier
; #define PG8_STAGE(bufoff, gbase, RR, ld) do { _Pragma("unroll") for (int _i = 0; _i < 2; ++_i) \
;         __builtin_amdgcn_global_load_lds((const unsigned*)((const char*)(gbase) + (RR)[_i] * (ld) + C2[_i]), (LAS unsigned*)(lds + (bufoff) + ldsw + _i * 8192), 16, 0, 0); } while (0)
; #define PG8_LDA(dst, b, h) do { _Pragma("unroll") for (int m = 0; m < 4; ++m) _Pragma("unroll") for (int k = 0; k < 2; ++k) dst[m][k] = *(const LAS bf16x8*)(lds + PG8_SA(b, h) + aoff + m * 2048 + k * 1024); } while (0)
; #define PG8_LDB(dst, b, h) do { _Pragma("unroll") for (int n = 0; n < 2; ++n) _Pragma("unroll") for (int k = 0; k < 2; ++k) dst[n][k] = *(const LAS bf16x8*)(lds + PG8_SB(b, h) + boff + n * 2048 + k * 1024); } while (0)
; #define PG8_MMA(ai, bj, At, Bt) do { __builtin_amdgcn_s_setprio(1); _Pragma("unroll") for (int m = 0; m < 4; ++m) _Pragma("unroll") for (int n = 0; n < 2; ++n) _Pragma("unroll") for (int k = 0; k < 2; ++k) \
;         acc[ai][bj][m][n] = __builtin_amdgcn_mfma_f32_16x16x32_bf16(Bt[n][k], At[m][k], acc[ai][bj][m][n], 0, 0, 0); __builtin_amdgcn_s_setprio(0); } while (0)
; #define PG8_WAIT_V(n) asm volatile("s_waitcnt vmcnt(" #n ")" ::: "memory")
; #define PG8_WAIT_L(n) asm volatile("s_waitcnt lgkmcnt(" #n ")" ::: "memory")
; #define PG8_BAR __builtin_amdgcn_s_barrier()
; #define PG8_SCHED __builtin_amdgcn_sched_barrier(0)
; template <class Sched, class Epi>
; __device__ __forceinline__ void gemm_run(LAS unsigned char* lds, const Sched& S, const Epi& E) {
;     ...
;             PG8_WAIT_V(8); PG8_WAIT_L(0); PG8_BAR; PG8_MMA(1, 0, At, B0); PG8_MMA(1, 1, At, B1); PG8_BAR; PG8_SCHED;
;             PG8_LDB(B0, 1, 0); PG8_LDB(B1, 1, 1); PG8_SCHED; PG8_LDA(At, 1, 0); PG8_STAGE(PG8_SA(0, 1), a2 + (size_t)HALF * la2, RA, la2);
;             PG8_WAIT_V(8); PG8_WAIT_L(0); PG8_BAR; PG8_MMA(0, 0, At, B0); PG8_MMA(0, 1, At, B1); PG8_BAR; PG8_SCHED;
	s_waitcnt lgkmcnt(0)
	v_mfma_f32_16x16x32_bf16 v[62:65], v[154:157], v[198:201], 0
	v_mfma_f32_16x16x32_bf16 v[58:61], v[162:165], v[198:201], 0
	v_mfma_f32_16x16x32_bf16 v[46:49], v[154:157], v[206:209], 0
	v_mfma_f32_16x16x32_bf16 v[42:45], v[162:165], v[206:209], 0
	v_mfma_f32_16x16x32_bf16 v[30:33], v[154:157], v[214:217], 0
	v_mfma_f32_16x16x32_bf16 v[26:29], v[162:165], v[214:217], 0
	v_mfma_f32_16x16x32_bf16 v[14:17], v[154:157], v[222:225], 0
	v_mfma_f32_16x16x32_bf16 v[10:13], v[162:165], v[222:225], 0
	v_mfma_f32_16x16x32_bf16 v[62:65], v[158:161], v[202:205], v[62:65]
	v_mfma_f32_16x16x32_bf16 v[58:61], v[166:169], v[202:205], v[58:61]
	v_mfma_f32_16x16x32_bf16 v[46:49], v[158:161], v[210:213], v[46:49]
	v_mfma_f32_16x16x32_bf16 v[42:45], v[166:169], v[210:213], v[42:45]
	v_mfma_f32_16x16x32_bf16 v[30:33], v[158:161], v[218:221], v[30:33]
	v_mfma_f32_16x16x32_bf16 v[26:29], v[166:169], v[218:221], v[26:29]
	v_mfma_f32_16x16x32_bf16 v[14:17], v[158:161], v[226:229], v[14:17]
	v_mfma_f32_16x16x32_bf16 v[10:13], v[166:169], v[226:229], v[10:13]
	v_mfma_f32_16x16x32_bf16 v[54:57], v[170:173], v[198:201], 0
	v_mfma_f32_16x16x32_bf16 v[50:53], v[190:193], v[198:201], 0
	v_mfma_f32_16x16x32_bf16 v[38:41], v[170:173], v[206:209], 0
	v_mfma_f32_16x16x32_bf16 v[34:37], v[190:193], v[206:209], 0
	v_mfma_f32_16x16x32_bf16 v[22:25], v[170:173], v[214:217], 0
	v_mfma_f32_16x16x32_bf16 v[18:21], v[190:193], v[214:217], 0
	v_mfma_f32_16x16x32_bf16 v[6:9], v[170:173], v[222:225], 0
	v_mfma_f32_16x16x32_bf16 v[2:5], v[190:193], v[222:225], 0
	v_mfma_f32_16x16x32_bf16 v[54:57], v[186:189], v[202:205], v[54:57]
	v_mfma_f32_16x16x32_bf16 v[50:53], v[194:197], v[202:205], v[50:53]
	v_mfma_f32_16x16x32_bf16 v[38:41], v[186:189], v[210:213], v[38:41]
	v_mfma_f32_16x16x32_bf16 v[34:37], v[194:197], v[210:213], v[34:37]
	v_mfma_f32_16x16x32_bf16 v[22:25], v[186:189], v[218:221], v[22:25]
	v_mfma_f32_16x16x32_bf16 v[18:21], v[194:197], v[218:221], v[18:21]
	v_mfma_f32_16x16x32_bf16 v[6:9], v[186:189], v[226:229], v[6:9]
	v_mfma_f32_16x16x32_bf16 v[2:5], v[194:197], v[226:229], v[2:5]
	s_barrier
	s_add_i32 s39, 0, 0x18000
	v_add_u32_e32 v134, s39, v179
	s_add_i32 s42, 0, 0x1c000
	ds_read_b128 v[154:157], v134
	ds_read_b128 v[158:161], v134 offset:1024
	ds_read_b128 v[162:165], v134 offset:2048
	ds_read_b128 v[166:169], v134 offset:3072
	v_add_u32_e32 v134, s42, v179
	ds_read_b128 v[170:173], v134
	ds_read_b128 v[186:189], v134 offset:1024
	ds_read_b128 v[190:193], v134 offset:2048
	ds_read_b128 v[194:197], v134 offset:3072
	s_add_u32 s40, s58, 0x80000
	s_addc_u32 s41, s59, 0
	v_lshl_add_u64 v[236:237], s[40:41], 0, v[138:139]
	s_mov_b32 m0, s60
	v_lshl_add_u64 v[236:237], v[236:237], 0, v[130:131]
	ds_read_b128 v[198:201], v184 offset:32768
	ds_read_b128 v[202:205], v184 offset:33792
	ds_read_b128 v[206:209], v184 offset:34816
	ds_read_b128 v[210:213], v184 offset:35840
	ds_read_b128 v[214:217], v184 offset:36864
	ds_read_b128 v[218:221], v184 offset:37888
	ds_read_b128 v[222:225], v184 offset:38912
	ds_read_b128 v[226:229], v184 offset:39936
	global_load_lds_dwordx4 v[236:237], off
	v_lshl_add_u64 v[236:237], s[40:41], 0, v[140:141]
	v_lshl_add_u64 v[236:237], v[236:237], 0, v[130:131]
	s_mov_b32 m0, s61
	s_nop 0
	global_load_lds_dwordx4 v[236:237], off
	s_waitcnt vmcnt(8)
	s_waitcnt lgkmcnt(0)
	s_barrier
	s_waitcnt lgkmcnt(0)
	v_mfma_f32_16x16x32_bf16 v[126:129], v[154:157], v[198:201], v[126:129]
	v_mfma_f32_16x16x32_bf16 v[122:125], v[162:165], v[198:201], v[122:125]
	v_mfma_f32_16x16x32_bf16 v[110:113], v[154:157], v[206:209], v[110:113]
	v_mfma_f32_16x16x32_bf16 v[106:109], v[162:165], v[206:209], v[106:109]
	v_mfma_f32_16x16x32_bf16 v[94:97], v[154:157], v[214:217], v[94:97]
	v_mfma_f32_16x16x32_bf16 v[90:93], v[162:165], v[214:217], v[90:93]
	v_mfma_f32_16x16x32_bf16 v[78:81], v[154:157], v[222:225], v[78:81]
	v_mfma_f32_16x16x32_bf16 v[74:77], v[162:165], v[222:225], v[74:77]
	v_mfma_f32_16x16x32_bf16 v[126:129], v[158:161], v[202:205], v[126:129]
	v_mfma_f32_16x16x32_bf16 v[122:125], v[166:169], v[202:205], v[122:125]
	v_mfma_f32_16x16x32_bf16 v[110:113], v[158:161], v[210:213], v[110:113]
	v_mfma_f32_16x16x32_bf16 v[106:109], v[166:169], v[210:213], v[106:109]
	v_mfma_f32_16x16x32_bf16 v[94:97], v[158:161], v[218:221], v[94:97]
	v_mfma_f32_16x16x32_bf16 v[90:93], v[166:169], v[218:221], v[90:93]
	v_mfma_f32_16x16x32_bf16 v[78:81], v[158:161], v[226:229], v[78:81]
	v_mfma_f32_16x16x32_bf16 v[74:77], v[166:169], v[226:229], v[74:77]
	v_mfma_f32_16x16x32_bf16 v[118:121], v[170:173], v[198:201], v[118:121]
	v_mfma_f32_16x16x32_bf16 v[114:117], v[190:193], v[198:201], v[114:117]
	v_mfma_f32_16x16x32_bf16 v[102:105], v[170:173], v[206:209], v[102:105]
	v_mfma_f32_16x16x32_bf16 v[98:101], v[190:193], v[206:209], v[98:101]
	v_mfma_f32_16x16x32_bf16 v[86:89], v[170:173], v[214:217], v[86:89]
	v_mfma_f32_16x16x32_bf16 v[82:85], v[190:193], v[214:217], v[82:85]
	v_mfma_f32_16x16x32_bf16 v[70:73], v[170:173], v[222:225], v[70:73]
	v_mfma_f32_16x16x32_bf16 v[66:69], v[190:193], v[222:225], v[66:69]
	v_mfma_f32_16x16x32_bf16 v[118:121], v[186:189], v[202:205], v[118:121]
	v_mfma_f32_16x16x32_bf16 v[114:117], v[194:197], v[202:205], v[114:117]
	v_mfma_f32_16x16x32_bf16 v[102:105], v[186:189], v[210:213], v[102:105]
	v_mfma_f32_16x16x32_bf16 v[98:101], v[194:197], v[210:213], v[98:101]
	v_mfma_f32_16x16x32_bf16 v[86:89], v[186:189], v[218:221], v[86:89]
	v_mfma_f32_16x16x32_bf16 v[82:85], v[194:197], v[218:221], v[82:85]
	v_mfma_f32_16x16x32_bf16 v[70:73], v[186:189], v[226:229], v[70:73]
	v_mfma_f32_16x16x32_bf16 v[66:69], v[194:197], v[226:229], v[66:69]
	s_barrier
; #define PG8_STAGE(bufoff, gbase, RR, ld) do { _Pragma("unroll") for (int _i = 0; _i < 2; ++_i) \
;         __builtin_amdgcn_global_load_lds((const unsigned*)((const char*)(gbase) + (RR)[_i] * (ld) + C2[_i]), (LAS unsigned*)(lds + (bufoff) + ldsw + _i * 8192), 16, 0, 0); } while (0)
; #define PG8_LDA(dst, b, h) do { _Pragma("unroll") for (int m = 0; m < 4; ++m) _Pragma("unroll") for (int k = 0; k < 2; ++k) dst[m][k] = *(const LAS bf16x8*)(lds + PG8_SA(b, h) + aoff + m * 2048 + k * 1024); } while (0)
; #define PG8_MMA(ai, bj, At, Bt) do { __builtin_amdgcn_s_setprio(1); _Pragma("unroll") for (int m = 0; m < 4; ++m) _Pragma("unroll") for (int n = 0; n < 2; ++n) _Pragma("unroll") for (int k = 0; k < 2; ++k) \
;         acc[ai][bj][m][n] = __builtin_amdgcn_mfma_f32_16x16x32_bf16(Bt[n][k], At[m][k], acc[ai][bj][m][n], 0, 0, 0); __builtin_amdgcn_s_setprio(0); } while (0)
; #define PG8_WAIT_V(n) asm volatile("s_waitcnt vmcnt(" #n ")" ::: "memory")
; #define PG8_WAIT_L(n) asm volatile("s_waitcnt lgkmcnt(" #n ")" ::: "memory")
; #define PG8_BAR __builtin_amdgcn_s_barrier()
; #define PG8_SCHED __builtin_amdgcn_sched_barrier(0)
; template <class Sched, class Epi>
; __device__ __forceinline__ void gemm_run(LAS unsigned char* lds, const Sched& S, const Epi& E) {
;     ...
;             PG8_LDA(At, 1, 1); PG8_STAGE(PG8_SB(1, 0), b3, RB, lb2); PG8_STAGE(PG8_SB(1, 1), b3 + (size_t)HALF * lb2, RB, lb2); PG8_STAGE(PG8_SA(1, 0), a3, RA, la2);
;             PG8_WAIT_V(8); PG8_WAIT_L(0); PG8_BAR; PG8_MMA(1, 0, At, B0); PG8_MMA(1, 1, At, B1); PG8_BAR; PG8_SCHED;
;         }
	s_add_i32 s39, s39, s3
	v_lshl_add_u64 v[174:175], v[174:175], 0, s[14:15]
	s_mov_b32 m0, s39
	ds_read_b128 v[198:201], v184 offset:49152
	ds_read_b128 v[202:205], v184 offset:50176
	ds_read_b128 v[206:209], v184 offset:51200
	ds_read_b128 v[210:213], v184 offset:52224
	ds_read_b128 v[214:217], v184 offset:53248
	ds_read_b128 v[218:221], v184 offset:54272
	ds_read_b128 v[222:225], v184 offset:55296
	ds_read_b128 v[226:229], v184 offset:56320
	global_load_lds_dwordx4 v[174:175], off
	s_add_i32 m0, s39, 0x2000
	s_add_u32 s40, s56, 0x80080
	v_lshl_add_u64 v[174:175], v[230:231], 0, s[14:15]
	s_addc_u32 s41, s57, 0
	global_load_lds_dwordx4 v[174:175], off
	v_lshl_add_u64 v[174:175], s[40:41], 0, v[132:133]
	s_add_i32 s39, s42, s3
	v_lshl_add_u64 v[174:175], v[174:175], 0, v[130:131]
	s_mov_b32 m0, s39
	s_nop 0
	global_load_lds_dwordx4 v[174:175], off
	v_lshl_add_u64 v[174:175], s[40:41], 0, v[136:137]
	v_lshl_add_u64 v[174:175], v[174:175], 0, v[130:131]
	s_add_i32 m0, s39, 0x2000
	s_nop 0
	global_load_lds_dwordx4 v[174:175], off
	v_lshl_add_u64 v[174:175], v[232:233], 0, s[14:15]
	s_mov_b32 m0, s64
	s_nop 0
	global_load_lds_dwordx4 v[174:175], off
	v_lshl_add_u64 v[174:175], v[234:235], 0, s[14:15]
	s_mov_b32 m0, s65
	s_nop 0
	global_load_lds_dwordx4 v[174:175], off
	s_waitcnt vmcnt(8)
	s_waitcnt lgkmcnt(0)
	s_barrier
	s_waitcnt lgkmcnt(0)
	v_mfma_f32_16x16x32_bf16 v[62:65], v[154:157], v[198:201], v[62:65]
	v_mfma_f32_16x16x32_bf16 v[58:61], v[162:165], v[198:201], v[58:61]
	v_mfma_f32_16x16x32_bf16 v[46:49], v[154:157], v[206:209], v[46:49]
	v_mfma_f32_16x16x32_bf16 v[42:45], v[162:165], v[206:209], v[42:45]
	v_mfma_f32_16x16x32_bf16 v[30:33], v[154:157], v[214:217], v[30:33]
	v_mfma_f32_16x16x32_bf16 v[26:29], v[162:165], v[214:217], v[26:29]
	v_mfma_f32_16x16x32_bf16 v[14:17], v[154:157], v[222:225], v[14:17]
	v_mfma_f32_16x16x32_bf16 v[10:13], v[162:165], v[222:225], v[10:13]
	v_mfma_f32_16x16x32_bf16 v[62:65], v[158:161], v[202:205], v[62:65]
	v_mfma_f32_16x16x32_bf16 v[58:61], v[166:169], v[202:205], v[58:61]
	v_mfma_f32_16x16x32_bf16 v[46:49], v[158:161], v[210:213], v[46:49]
	v_mfma_f32_16x16x32_bf16 v[42:45], v[166:169], v[210:213], v[42:45]
	v_mfma_f32_16x16x32_bf16 v[30:33], v[158:161], v[218:221], v[30:33]
	v_mfma_f32_16x16x32_bf16 v[26:29], v[166:169], v[218:221], v[26:29]
	v_mfma_f32_16x16x32_bf16 v[14:17], v[158:161], v[226:229], v[14:17]
	v_mfma_f32_16x16x32_bf16 v[10:13], v[166:169], v[226:229], v[10:13]
	v_mfma_f32_16x16x32_bf16 v[54:57], v[170:173], v[198:201], v[54:57]
	v_mfma_f32_16x16x32_bf16 v[50:53], v[190:193], v[198:201], v[50:53]
	v_mfma_f32_16x16x32_bf16 v[38:41], v[170:173], v[206:209], v[38:41]
	v_mfma_f32_16x16x32_bf16 v[34:37], v[190:193], v[206:209], v[34:37]
	v_mfma_f32_16x16x32_bf16 v[22:25], v[170:173], v[214:217], v[22:25]
	v_mfma_f32_16x16x32_bf16 v[18:21], v[190:193], v[214:217], v[18:21]
	v_mfma_f32_16x16x32_bf16 v[6:9], v[170:173], v[222:225], v[6:9]
	v_mfma_f32_16x16x32_bf16 v[2:5], v[190:193], v[222:225], v[2:5]
	v_mfma_f32_16x16x32_bf16 v[54:57], v[186:189], v[202:205], v[54:57]
	v_mfma_f32_16x16x32_bf16 v[50:53], v[194:197], v[202:205], v[50:53]
	v_mfma_f32_16x16x32_bf16 v[38:41], v[186:189], v[210:213], v[38:41]
	v_mfma_f32_16x16x32_bf16 v[34:37], v[194:197], v[210:213], v[34:37]
	v_mfma_f32_16x16x32_bf16 v[22:25], v[186:189], v[218:221], v[22:25]
	v_mfma_f32_16x16x32_bf16 v[18:21], v[194:197], v[218:221], v[18:21]
	v_mfma_f32_16x16x32_bf16 v[6:9], v[186:189], v[226:229], v[6:9]
	v_mfma_f32_16x16x32_bf16 v[2:5], v[194:197], v[226:229], v[2:5]
	s_barrier
	s_add_i32 s38, s38, 2
	s_add_u32 s54, s54, 0x100
	s_addc_u32 s55, s55, 0
	s_cmp_gt_u32 s38, 29
	s_cbranch_scc0 .LBB0_246
	.p2align 6

; #define PG8_STAGE(bufoff, gbase, RR, ld) do { _Pragma("unroll") for (int _i = 0; _i < 2; ++_i) \
;         __builtin_amdgcn_global_load_lds((const unsigned*)((const char*)(gbase) + (RR)[_i] * (ld) + C2[_i]), (LAS unsigned*)(lds + (bufoff) + ldsw + _i * 8192), 16, 0, 0); } while (0)
; #define PG8_LDA(dst, b, h) do { _Pragma("unroll") for (int m = 0; m < 4; ++m) _Pragma("unroll") for (int k = 0; k < 2; ++k) dst[m][k] = *(const LAS bf16x8*)(lds + PG8_SA(b, h) + aoff + m * 2048 + k * 1024); } while (0)
; #define PG8_LDB(dst, b, h) do { _Pragma("unroll") for (int n = 0; n < 2; ++n) _Pragma("unroll") for (int k = 0; k < 2; ++k) dst[n][k] = *(const LAS bf16x8*)(lds + PG8_SB(b, h) + boff + n * 2048 + k * 1024); } while (0)
; #define PG8_WAIT_V(n) asm volatile("s_waitcnt vmcnt(" #n ")" ::: "memory")
; template <class Sched, class Epi>
; __device__ __forceinline__ void gemm_run(LAS unsigned char* lds, const Sched& S, const Epi& E) {
;     ...
;     f32x4 acc[2][2][4][2];
; #pragma unroll
;     for (int a = 0; a < 2; ++a)
; #pragma unroll
;         for (int b = 0; b < 2; ++b)
; #pragma unroll
;             for (int m = 0; m < 4; ++m)
; #pragma unroll
;                 for (int n = 0; n < 2; ++n) acc[a][b][m][n] = (f32x4){0.f, 0.f, 0.f, 0.f};
;     ...
;     for (;;) {
;         const bool has_next = S.next(ui + 1, nxt);
;         const char* nA = has_next ? nxt.A : cA; const char* nB = has_next ? nxt.B : cB; const unsigned nlda = has_next ? nxt.lda : lda, nldb = has_next ? nxt.ldb : ldb;
;         const int nt = cur.nt;
;         for (int t = 0; t < nt; t += 2) {
;             const bool last = (t == nt - 2);
;             const char* a1 = cA + (size_t)(t + 1) * kstep;
;             const char* a2 = last ? nA : cA + (size_t)(t + 2) * kstep; const char* b2 = last ? nB : cB + (size_t)(t + 2) * kstep;
;             const unsigned la2 = last ? nlda : lda, lb2 = last ? nldb : ldb;
;             const char* a3 = a2 + kstep; const char* b3 = b2 + kstep;
;             PG8_LDB(B0, 0, 0); PG8_LDB(B1, 0, 1); PG8_SCHED; PG8_LDA(At, 0, 0); PG8_STAGE(PG8_SA(1, 1), a1 + (size_t)HALF * lda, RA, lda);
;             PG8_WAIT_V(8); PG8_WAIT_L(0); PG8_BAR; PG8_MMA(0, 0, At, B0); PG8_MMA(0, 1, At, B1); PG8_BAR; PG8_SCHED;
;             PG8_LDA(At, 0, 1); PG8_STAGE(PG8_SB(0, 0), b2, RB, lb2); PG8_STAGE(PG8_SB(0, 1), b2 + (size_t)HALF * lb2, RB, lb2); PG8_STAGE(PG8_SA(0, 0), a2, RA, la2);
.LBB0_439:
	s_and_b64 s[38:39], s[36:37], exec
	s_mov_b32 s63, s1
	s_cselect_b32 s55, s29, s59
	s_cselect_b32 s61, s28, s58
	s_cselect_b32 vcc_lo, s31, s65
	s_cselect_b32 vcc_hi, s30, s64
	s_lshl_b64 s[42:43], s[62:63], 7
	v_mul_lo_u32 v148, v177, s62
	v_lshl_add_u64 v[2:3], s[58:59], 0, v[160:161]
	v_lshl_add_u64 v[4:5], s[42:43], 0, v[148:149]
	v_mul_lo_u32 v148, v178, s62
	s_add_i32 s38, s5, -2
	v_lshl_add_u64 v[130:131], v[2:3], 0, v[4:5]
	v_lshl_add_u64 v[4:5], s[42:43], 0, v[148:149]
	s_add_u32 s39, s64, 0x100
	v_lshl_add_u64 v[132:133], v[2:3], 0, v[4:5]
	s_addc_u32 s40, s65, 0
	s_mov_b64 s[64:65], 0
	s_add_i32 s41, s0, 2
	s_add_u32 s42, s58, s64
	s_addc_u32 s43, s59, s65
	ds_read_b128 v[134:137], v179
	ds_read_b128 v[138:141], v179 offset:1024
	ds_read_b128 v[142:145], v179 offset:2048
	ds_read_b128 v[162:165], v179 offset:3072
	ds_read_b128 v[166:169], v180
	ds_read_b128 v[186:189], v180 offset:1024
	ds_read_b128 v[190:193], v180 offset:2048
	ds_read_b128 v[194:197], v180 offset:3072
	s_add_u32 s46, s42, 0x100
	s_addc_u32 s47, s43, 0
	s_add_u32 s48, s39, s64
	s_addc_u32 s49, s40, s65
	s_cmp_eq_u32 s38, s0
	s_cselect_b64 s[42:43], -1, 0
	s_and_b64 s[44:45], s[42:43], exec
	s_cselect_b32 s67, s55, s47
	s_cselect_b32 s66, s61, s46
	s_cselect_b32 s71, vcc_lo, s49
	s_cselect_b32 s70, vcc_hi, s48
	s_and_b64 s[42:43], s[36:37], s[42:43]
	s_and_b64 s[42:43], s[42:43], exec
	s_cselect_b32 s0, s3, s60
	s_cselect_b32 s68, s4, s62
	v_lshl_add_u64 v[170:171], v[130:131], 0, s[64:65]
	s_add_i32 m0, s82, 0xc000
	ds_read_b128 v[198:201], v181
	ds_read_b128 v[202:205], v181 offset:1024
	ds_read_b128 v[206:209], v181 offset:2048
	ds_read_b128 v[210:213], v181 offset:3072
	ds_read_b128 v[214:217], v181 offset:4096
	ds_read_b128 v[218:221], v181 offset:5120
	ds_read_b128 v[222:225], v181 offset:6144
	ds_read_b128 v[226:229], v181 offset:7168
	global_load_lds_dwordx4 v[170:171], off
	v_lshl_add_u64 v[170:171], v[132:133], 0, s[64:65]
	s_add_i32 m0, s82, 0xe000
	s_nop 0
	global_load_lds_dwordx4 v[170:171], off
	s_waitcnt vmcnt(8)
	s_waitcnt lgkmcnt(0)
	s_barrier
	s_waitcnt lgkmcnt(0)
	v_mfma_f32_16x16x32_bf16 v[126:129], v[134:137], v[198:201], 0
	v_mfma_f32_16x16x32_bf16 v[122:125], v[142:145], v[198:201], 0
	v_mfma_f32_16x16x32_bf16 v[110:113], v[134:137], v[206:209], 0
	v_mfma_f32_16x16x32_bf16 v[106:109], v[142:145], v[206:209], 0
	v_mfma_f32_16x16x32_bf16 v[94:97], v[134:137], v[214:217], 0
	v_mfma_f32_16x16x32_bf16 v[90:93], v[142:145], v[214:217], 0
	v_mfma_f32_16x16x32_bf16 v[78:81], v[134:137], v[222:225], 0
	v_mfma_f32_16x16x32_bf16 v[74:77], v[142:145], v[222:225], 0
	v_mfma_f32_16x16x32_bf16 v[126:129], v[138:141], v[202:205], v[126:129]
	v_mfma_f32_16x16x32_bf16 v[122:125], v[162:165], v[202:205], v[122:125]
	v_mfma_f32_16x16x32_bf16 v[110:113], v[138:141], v[210:213], v[110:113]
	v_mfma_f32_16x16x32_bf16 v[106:109], v[162:165], v[210:213], v[106:109]
	v_mfma_f32_16x16x32_bf16 v[94:97], v[138:141], v[218:221], v[94:97]
	v_mfma_f32_16x16x32_bf16 v[90:93], v[162:165], v[218:221], v[90:93]
	v_mfma_f32_16x16x32_bf16 v[78:81], v[138:141], v[226:229], v[78:81]
	v_mfma_f32_16x16x32_bf16 v[74:77], v[162:165], v[226:229], v[74:77]
	v_mfma_f32_16x16x32_bf16 v[118:121], v[166:169], v[198:201], 0
	v_mfma_f32_16x16x32_bf16 v[114:117], v[190:193], v[198:201], 0
	v_mfma_f32_16x16x32_bf16 v[102:105], v[166:169], v[206:209], 0
	v_mfma_f32_16x16x32_bf16 v[98:101], v[190:193], v[206:209], 0
	v_mfma_f32_16x16x32_bf16 v[86:89], v[166:169], v[214:217], 0
	v_mfma_f32_16x16x32_bf16 v[82:85], v[190:193], v[214:217], 0
	v_mfma_f32_16x16x32_bf16 v[70:73], v[166:169], v[222:225], 0
	v_mfma_f32_16x16x32_bf16 v[66:69], v[190:193], v[222:225], 0
	v_mfma_f32_16x16x32_bf16 v[118:121], v[186:189], v[202:205], v[118:121]
	v_mfma_f32_16x16x32_bf16 v[114:117], v[194:197], v[202:205], v[114:117]
	v_mfma_f32_16x16x32_bf16 v[102:105], v[186:189], v[210:213], v[102:105]
	v_mfma_f32_16x16x32_bf16 v[98:101], v[194:197], v[210:213], v[98:101]
	v_mfma_f32_16x16x32_bf16 v[86:89], v[186:189], v[218:221], v[86:89]
	v_mfma_f32_16x16x32_bf16 v[82:85], v[194:197], v[218:221], v[82:85]
	v_mfma_f32_16x16x32_bf16 v[70:73], v[186:189], v[226:229], v[70:73]
	v_mfma_f32_16x16x32_bf16 v[66:69], v[194:197], v[226:229], v[66:69]
	s_barrier
	v_mul_lo_u32 v148, s0, v173
	v_lshl_add_u64 v[170:171], s[70:71], 0, v[148:149]
	s_add_i32 s42, s97, s81
	v_lshl_add_u64 v[170:171], v[170:171], 0, v[146:147]
	s_mov_b32 m0, s42
	ds_read_b128 v[198:201], v181 offset:16384
	ds_read_b128 v[202:205], v181 offset:17408
	ds_read_b128 v[206:209], v181 offset:18432
	ds_read_b128 v[210:213], v181 offset:19456
	ds_read_b128 v[214:217], v181 offset:20480
	ds_read_b128 v[218:221], v181 offset:21504
	ds_read_b128 v[222:225], v181 offset:22528
	ds_read_b128 v[226:229], v181 offset:23552
	global_load_lds_dwordx4 v[170:171], off
	s_add_i32 m0, s42, 0x2000
	s_lshl_b64 s[42:43], s[0:1], 7
	v_mul_lo_u32 v230, s0, v175
	v_mov_b32_e32 v231, v149
	s_add_u32 s42, s70, s42
	v_lshl_add_u64 v[232:233], s[70:71], 0, v[230:231]
	s_addc_u32 s43, s71, s43
	v_lshl_add_u64 v[232:233], v[232:233], 0, v[146:147]
	v_lshl_add_u64 v[234:235], s[42:43], 0, v[148:149]
	s_add_i32 s0, s33, s81
	global_load_lds_dwordx4 v[232:233], off
	v_lshl_add_u64 v[234:235], v[234:235], 0, v[146:147]
	s_mov_b32 m0, s0
	v_lshl_add_u64 v[230:231], s[42:43], 0, v[230:231]
	v_mul_lo_u32 v148, s68, v172
	global_load_lds_dwordx4 v[234:235], off
	v_lshl_add_u64 v[230:231], v[230:231], 0, v[146:147]
	s_add_i32 m0, s0, 0x2000
	v_lshl_add_u64 v[236:237], s[66:67], 0, v[148:149]
	v_mul_lo_u32 v238, s68, v174
	v_mov_b32_e32 v239, v149
	global_load_lds_dwordx4 v[230:231], off
	v_lshl_add_u64 v[236:237], v[236:237], 0, v[146:147]
	s_mov_b32 m0, s82
	v_lshl_add_u64 v[240:241], s[66:67], 0, v[238:239]
	global_load_lds_dwordx4 v[236:237], off
	v_lshl_add_u64 v[240:241], v[240:241], 0, v[146:147]
	s_mov_b32 m0, s83
	s_nop 0
	global_load_lds_dwordx4 v[240:241], off
	s_waitcnt vmcnt(8)
	s_waitcnt lgkmcnt(0)
	s_barrier
; #define PG8_STAGE(bufoff, gbase, RR, ld) do { _Pragma("unroll") for (int _i = 0; _i < 2; ++_i) \
;         __builtin_amdgcn_global_load_lds((const unsigned*)((const char*)(gbase) + (RR)[_i] * (ld) + C2[_i]), (LAS unsigned*)(lds + (bufoff) + ldsw + _i * 8192), 16, 0, 0); } while (0)
; #define PG8_LDA(dst, b, h) do { _Pragma("unroll") for (int m = 0; m < 4; ++m) _Pragma("unroll") for (int k = 0; k < 2; ++k) dst[m][k] = *(const LAS bf16x8*)(lds + PG8_SA(b, h) + aoff + m * 2048 + k * 1024); } while (0)
; #define PG8_LDB(dst, b, h) do { _Pragma("unroll") for (int n = 0; n < 2; ++n) _Pragma("unroll") for (int k = 0; k < 2; ++k) dst[n][k] = *(const LAS bf16x8*)(lds + PG8_SB(b, h) + boff + n * 2048 + k * 1024); } while (0)
; #define PG8_MMA(ai, bj, At, Bt) do { __builtin_amdgcn_s_setprio(1); _Pragma("unroll") for (int m = 0; m < 4; ++m) _Pragma("unroll") for (int n = 0; n < 2; ++n) _Pragma("unroll") for (int k = 0; k < 2; ++k) \
;         acc[ai][bj][m][n] = __builtin_amdgcn_mfma_f32_16x16x32_bf16(Bt[n][k], At[m][k], acc[ai][bj][m][n], 0, 0, 0); __builtin_amdgcn_s_setprio(0); } while (0)
; #define PG8_WAIT_V(n) asm volatile("s_waitcnt vmcnt(" #n ")" ::: "memory")
; #define PG8_WAIT_L(n) asm volatile("s_waitcnt lgkmcnt(" #n ")" ::: "memory")
; #define PG8_BAR __builtin_amdgcn_s_barrier()
; #define PG8_SCHED __builtin_amdgcn_sched_barrier(0)
; template <class Sched, class Epi>
; __device__ __forceinline__ void gemm_run(LAS unsigned char* lds, const Sched& S, const Epi& E) {
;     ...
;             PG8_WAIT_V(8); PG8_WAIT_L(0); PG8_BAR; PG8_MMA(1, 0, At, B0); PG8_MMA(1, 1, At, B1); PG8_BAR; PG8_SCHED;
;             PG8_LDB(B0, 1, 0); PG8_LDB(B1, 1, 1); PG8_SCHED; PG8_LDA(At, 1, 0); PG8_STAGE(PG8_SA(0, 1), a2 + (size_t)HALF * la2, RA, la2);
;             PG8_WAIT_V(8); PG8_WAIT_L(0); PG8_BAR; PG8_MMA(0, 0, At, B0); PG8_MMA(0, 1, At, B1); PG8_BAR; PG8_SCHED;
	s_waitcnt lgkmcnt(0)
	v_mfma_f32_16x16x32_bf16 v[62:65], v[134:137], v[198:201], 0
	v_mfma_f32_16x16x32_bf16 v[58:61], v[142:145], v[198:201], 0
	v_mfma_f32_16x16x32_bf16 v[46:49], v[134:137], v[206:209], 0
	v_mfma_f32_16x16x32_bf16 v[42:45], v[142:145], v[206:209], 0
	v_mfma_f32_16x16x32_bf16 v[30:33], v[134:137], v[214:217], 0
	v_mfma_f32_16x16x32_bf16 v[26:29], v[142:145], v[214:217], 0
	v_mfma_f32_16x16x32_bf16 v[14:17], v[134:137], v[222:225], 0
	v_mfma_f32_16x16x32_bf16 v[10:13], v[142:145], v[222:225], 0
	v_mfma_f32_16x16x32_bf16 v[62:65], v[138:141], v[202:205], v[62:65]
	v_mfma_f32_16x16x32_bf16 v[58:61], v[162:165], v[202:205], v[58:61]
	v_mfma_f32_16x16x32_bf16 v[46:49], v[138:141], v[210:213], v[46:49]
	v_mfma_f32_16x16x32_bf16 v[42:45], v[162:165], v[210:213], v[42:45]
	v_mfma_f32_16x16x32_bf16 v[30:33], v[138:141], v[218:221], v[30:33]
	v_mfma_f32_16x16x32_bf16 v[26:29], v[162:165], v[218:221], v[26:29]
	v_mfma_f32_16x16x32_bf16 v[14:17], v[138:141], v[226:229], v[14:17]
	v_mfma_f32_16x16x32_bf16 v[10:13], v[162:165], v[226:229], v[10:13]
	v_mfma_f32_16x16x32_bf16 v[54:57], v[166:169], v[198:201], 0
	v_mfma_f32_16x16x32_bf16 v[50:53], v[190:193], v[198:201], 0
	v_mfma_f32_16x16x32_bf16 v[38:41], v[166:169], v[206:209], 0
	v_mfma_f32_16x16x32_bf16 v[34:37], v[190:193], v[206:209], 0
	v_mfma_f32_16x16x32_bf16 v[22:25], v[166:169], v[214:217], 0
	v_mfma_f32_16x16x32_bf16 v[18:21], v[190:193], v[214:217], 0
	v_mfma_f32_16x16x32_bf16 v[6:9], v[166:169], v[222:225], 0
	v_mfma_f32_16x16x32_bf16 v[2:5], v[190:193], v[222:225], 0
	v_mfma_f32_16x16x32_bf16 v[54:57], v[186:189], v[202:205], v[54:57]
	v_mfma_f32_16x16x32_bf16 v[50:53], v[194:197], v[202:205], v[50:53]
	v_mfma_f32_16x16x32_bf16 v[38:41], v[186:189], v[210:213], v[38:41]
	v_mfma_f32_16x16x32_bf16 v[34:37], v[194:197], v[210:213], v[34:37]
	v_mfma_f32_16x16x32_bf16 v[22:25], v[186:189], v[218:221], v[22:25]
	v_mfma_f32_16x16x32_bf16 v[18:21], v[194:197], v[218:221], v[18:21]
	v_mfma_f32_16x16x32_bf16 v[6:9], v[186:189], v[226:229], v[6:9]
	v_mfma_f32_16x16x32_bf16 v[2:5], v[194:197], v[226:229], v[2:5]
	s_barrier
	s_add_i32 s0, 0, 0x18000
	s_add_i32 s44, 0, 0x1c000
	v_add_u32_e32 v162, s0, v176
	v_add_u32_e32 v185, s44, v176
	ds_read_b128 v[134:137], v162
	ds_read_b128 v[138:141], v162 offset:1024
	ds_read_b128 v[142:145], v162 offset:2048
	ds_read_b128 v[162:165], v162 offset:3072
	ds_read_b128 v[166:169], v185
	ds_read_b128 v[186:189], v185 offset:1024
	ds_read_b128 v[190:193], v185 offset:2048
	ds_read_b128 v[194:197], v185 offset:3072
	s_mov_b32 s69, s1
	s_lshl_b64 s[42:43], s[68:69], 7
	s_add_u32 s42, s66, s42
	s_addc_u32 s43, s67, s43
	v_lshl_add_u64 v[242:243], s[42:43], 0, v[148:149]
	s_mov_b32 m0, s85
	v_lshl_add_u64 v[242:243], v[242:243], 0, v[146:147]
	v_lshl_add_u64 v[238:239], s[42:43], 0, v[238:239]
	ds_read_b128 v[198:201], v181 offset:32768
	ds_read_b128 v[202:205], v181 offset:33792
	ds_read_b128 v[206:209], v181 offset:34816
	ds_read_b128 v[210:213], v181 offset:35840
	ds_read_b128 v[214:217], v181 offset:36864
	ds_read_b128 v[218:221], v181 offset:37888
	ds_read_b128 v[222:225], v181 offset:38912
	ds_read_b128 v[226:229], v181 offset:39936
	global_load_lds_dwordx4 v[242:243], off
	v_lshl_add_u64 v[238:239], v[238:239], 0, v[146:147]
	s_mov_b32 m0, s90
	s_nop 0
	global_load_lds_dwordx4 v[238:239], off
	s_waitcnt vmcnt(8)
	s_waitcnt lgkmcnt(0)
	s_barrier
	s_waitcnt lgkmcnt(0)
	v_mfma_f32_16x16x32_bf16 v[126:129], v[134:137], v[198:201], v[126:129]
	v_mfma_f32_16x16x32_bf16 v[122:125], v[142:145], v[198:201], v[122:125]
	v_mfma_f32_16x16x32_bf16 v[110:113], v[134:137], v[206:209], v[110:113]
	v_mfma_f32_16x16x32_bf16 v[106:109], v[142:145], v[206:209], v[106:109]
	v_mfma_f32_16x16x32_bf16 v[94:97], v[134:137], v[214:217], v[94:97]
	v_mfma_f32_16x16x32_bf16 v[90:93], v[142:145], v[214:217], v[90:93]
	v_mfma_f32_16x16x32_bf16 v[78:81], v[134:137], v[222:225], v[78:81]
	v_mfma_f32_16x16x32_bf16 v[74:77], v[142:145], v[222:225], v[74:77]
	v_mfma_f32_16x16x32_bf16 v[126:129], v[138:141], v[202:205], v[126:129]
	v_mfma_f32_16x16x32_bf16 v[122:125], v[162:165], v[202:205], v[122:125]
	v_mfma_f32_16x16x32_bf16 v[110:113], v[138:141], v[210:213], v[110:113]
	v_mfma_f32_16x16x32_bf16 v[106:109], v[162:165], v[210:213], v[106:109]
	v_mfma_f32_16x16x32_bf16 v[94:97], v[138:141], v[218:221], v[94:97]
	v_mfma_f32_16x16x32_bf16 v[90:93], v[162:165], v[218:221], v[90:93]
	v_mfma_f32_16x16x32_bf16 v[78:81], v[138:141], v[226:229], v[78:81]
	v_mfma_f32_16x16x32_bf16 v[74:77], v[162:165], v[226:229], v[74:77]
	v_mfma_f32_16x16x32_bf16 v[118:121], v[166:169], v[198:201], v[118:121]
	v_mfma_f32_16x16x32_bf16 v[114:117], v[190:193], v[198:201], v[114:117]
	v_mfma_f32_16x16x32_bf16 v[102:105], v[166:169], v[206:209], v[102:105]
	v_mfma_f32_16x16x32_bf16 v[98:101], v[190:193], v[206:209], v[98:101]
	v_mfma_f32_16x16x32_bf16 v[86:89], v[166:169], v[214:217], v[86:89]
	v_mfma_f32_16x16x32_bf16 v[82:85], v[190:193], v[214:217], v[82:85]
	v_mfma_f32_16x16x32_bf16 v[70:73], v[166:169], v[222:225], v[70:73]
	v_mfma_f32_16x16x32_bf16 v[66:69], v[190:193], v[222:225], v[66:69]
	v_mfma_f32_16x16x32_bf16 v[118:121], v[186:189], v[202:205], v[118:121]
	v_mfma_f32_16x16x32_bf16 v[114:117], v[194:197], v[202:205], v[114:117]
	v_mfma_f32_16x16x32_bf16 v[102:105], v[186:189], v[210:213], v[102:105]
	v_mfma_f32_16x16x32_bf16 v[98:101], v[194:197], v[210:213], v[98:101]
	v_mfma_f32_16x16x32_bf16 v[86:89], v[186:189], v[218:221], v[86:89]
	v_mfma_f32_16x16x32_bf16 v[82:85], v[194:197], v[218:221], v[82:85]
	v_mfma_f32_16x16x32_bf16 v[70:73], v[186:189], v[226:229], v[70:73]
	v_mfma_f32_16x16x32_bf16 v[66:69], v[194:197], v[226:229], v[66:69]
	s_barrier
; #define PG8_STAGE(bufoff, gbase, RR, ld) do { _Pragma("unroll") for (int _i = 0; _i < 2; ++_i) \
;         __builtin_amdgcn_global_load_lds((const unsigned*)((const char*)(gbase) + (RR)[_i] * (ld) + C2[_i]), (LAS unsigned*)(lds + (bufoff) + ldsw + _i * 8192), 16, 0, 0); } while (0)
; #define PG8_LDA(dst, b, h) do { _Pragma("unroll") for (int m = 0; m < 4; ++m) _Pragma("unroll") for (int k = 0; k < 2; ++k) dst[m][k] = *(const LAS bf16x8*)(lds + PG8_SA(b, h) + aoff + m * 2048 + k * 1024); } while (0)
; #define PG8_MMA(ai, bj, At, Bt) do { __builtin_amdgcn_s_setprio(1); _Pragma("unroll") for (int m = 0; m < 4; ++m) _Pragma("unroll") for (int n = 0; n < 2; ++n) _Pragma("unroll") for (int k = 0; k < 2; ++k) \
;         acc[ai][bj][m][n] = __builtin_amdgcn_mfma_f32_16x16x32_bf16(Bt[n][k], At[m][k], acc[ai][bj][m][n], 0, 0, 0); __builtin_amdgcn_s_setprio(0); } while (0)
; #define PG8_WAIT_V(n) asm volatile("s_waitcnt vmcnt(" #n ")" ::: "memory")
; #define PG8_WAIT_L(n) asm volatile("s_waitcnt lgkmcnt(" #n ")" ::: "memory")
; #define PG8_BAR __builtin_amdgcn_s_barrier()
; #define PG8_SCHED __builtin_amdgcn_sched_barrier(0)
; template <class Sched, class Epi>
; __device__ __forceinline__ void gemm_run(LAS unsigned char* lds, const Sched& S, const Epi& E) {
;     ...
;             PG8_LDA(At, 1, 1); PG8_STAGE(PG8_SB(1, 0), b3, RB, lb2); PG8_STAGE(PG8_SB(1, 1), b3 + (size_t)HALF * lb2, RB, lb2); PG8_STAGE(PG8_SA(1, 0), a3, RA, la2);
;             PG8_WAIT_V(8); PG8_WAIT_L(0); PG8_BAR; PG8_MMA(1, 0, At, B0); PG8_MMA(1, 1, At, B1); PG8_BAR; PG8_SCHED;
;         }
	s_add_i32 s0, s0, s81
	v_lshl_add_u64 v[170:171], v[170:171], 0, s[8:9]
	s_mov_b32 m0, s0
	ds_read_b128 v[198:201], v181 offset:49152
	ds_read_b128 v[202:205], v181 offset:50176
	ds_read_b128 v[206:209], v181 offset:51200
	ds_read_b128 v[210:213], v181 offset:52224
	ds_read_b128 v[214:217], v181 offset:53248
	ds_read_b128 v[218:221], v181 offset:54272
	ds_read_b128 v[222:225], v181 offset:55296
	ds_read_b128 v[226:229], v181 offset:56320
	global_load_lds_dwordx4 v[170:171], off
	v_lshl_add_u64 v[170:171], v[232:233], 0, s[8:9]
	s_add_i32 m0, s0, 0x2000
	s_add_i32 s0, s44, s81
	global_load_lds_dwordx4 v[170:171], off
	v_lshl_add_u64 v[170:171], v[234:235], 0, s[8:9]
	s_mov_b32 m0, s0
	s_nop 0
	global_load_lds_dwordx4 v[170:171], off
	v_lshl_add_u64 v[170:171], v[230:231], 0, s[8:9]
	s_add_i32 m0, s0, 0x2000
	s_nop 0
	global_load_lds_dwordx4 v[170:171], off
	v_lshl_add_u64 v[170:171], v[236:237], 0, s[8:9]
	s_mov_b32 m0, s93
	s_nop 0
	global_load_lds_dwordx4 v[170:171], off
	v_lshl_add_u64 v[170:171], v[240:241], 0, s[8:9]
	s_mov_b32 m0, s94
	s_nop 0
	global_load_lds_dwordx4 v[170:171], off
	s_waitcnt vmcnt(8)
	s_waitcnt lgkmcnt(0)
	s_barrier
	s_waitcnt lgkmcnt(0)
	v_mfma_f32_16x16x32_bf16 v[62:65], v[134:137], v[198:201], v[62:65]
	v_mfma_f32_16x16x32_bf16 v[58:61], v[142:145], v[198:201], v[58:61]
	v_mfma_f32_16x16x32_bf16 v[46:49], v[134:137], v[206:209], v[46:49]
	v_mfma_f32_16x16x32_bf16 v[42:45], v[142:145], v[206:209], v[42:45]
	v_mfma_f32_16x16x32_bf16 v[30:33], v[134:137], v[214:217], v[30:33]
	v_mfma_f32_16x16x32_bf16 v[26:29], v[142:145], v[214:217], v[26:29]
	v_mfma_f32_16x16x32_bf16 v[14:17], v[134:137], v[222:225], v[14:17]
	v_mfma_f32_16x16x32_bf16 v[10:13], v[142:145], v[222:225], v[10:13]
	v_mfma_f32_16x16x32_bf16 v[62:65], v[138:141], v[202:205], v[62:65]
	v_mfma_f32_16x16x32_bf16 v[58:61], v[162:165], v[202:205], v[58:61]
	v_mfma_f32_16x16x32_bf16 v[46:49], v[138:141], v[210:213], v[46:49]
	v_mfma_f32_16x16x32_bf16 v[42:45], v[162:165], v[210:213], v[42:45]
	v_mfma_f32_16x16x32_bf16 v[30:33], v[138:141], v[218:221], v[30:33]
	v_mfma_f32_16x16x32_bf16 v[26:29], v[162:165], v[218:221], v[26:29]
	v_mfma_f32_16x16x32_bf16 v[14:17], v[138:141], v[226:229], v[14:17]
	v_mfma_f32_16x16x32_bf16 v[10:13], v[162:165], v[226:229], v[10:13]
	v_mfma_f32_16x16x32_bf16 v[54:57], v[166:169], v[198:201], v[54:57]
	v_mfma_f32_16x16x32_bf16 v[50:53], v[190:193], v[198:201], v[50:53]
	v_mfma_f32_16x16x32_bf16 v[38:41], v[166:169], v[206:209], v[38:41]
	v_mfma_f32_16x16x32_bf16 v[34:37], v[190:193], v[206:209], v[34:37]
	v_mfma_f32_16x16x32_bf16 v[22:25], v[166:169], v[214:217], v[22:25]
	v_mfma_f32_16x16x32_bf16 v[18:21], v[190:193], v[214:217], v[18:21]
	v_mfma_f32_16x16x32_bf16 v[6:9], v[166:169], v[222:225], v[6:9]
	v_mfma_f32_16x16x32_bf16 v[2:5], v[190:193], v[222:225], v[2:5]
	v_mfma_f32_16x16x32_bf16 v[54:57], v[186:189], v[202:205], v[54:57]
	v_mfma_f32_16x16x32_bf16 v[50:53], v[194:197], v[202:205], v[50:53]
	v_mfma_f32_16x16x32_bf16 v[38:41], v[186:189], v[210:213], v[38:41]
	v_mfma_f32_16x16x32_bf16 v[34:37], v[194:197], v[210:213], v[34:37]
	v_mfma_f32_16x16x32_bf16 v[22:25], v[186:189], v[218:221], v[22:25]
	v_mfma_f32_16x16x32_bf16 v[18:21], v[194:197], v[218:221], v[18:21]
	v_mfma_f32_16x16x32_bf16 v[6:9], v[186:189], v[226:229], v[6:9]
	v_mfma_f32_16x16x32_bf16 v[2:5], v[194:197], v[226:229], v[2:5]
	s_barrier
	s_add_u32 s64, s64, 0x100
	s_addc_u32 s65, s65, 0
	s_cmp_ge_i32 s41, s5
	s_mov_b32 s0, s41
	s_cbranch_scc0 .LBB0_440
	.p2align 6

; #define PG8_STAGE(bufoff, gbase, RR, ld) do { _Pragma("unroll") for (int _i = 0; _i < 2; ++_i) \
;         __builtin_amdgcn_global_load_lds((const unsigned*)((const char*)(gbase) + (RR)[_i] * (ld) + C2[_i]), (LAS unsigned*)(lds + (bufoff) + ldsw + _i * 8192), 16, 0, 0); } while (0)
; #define PG8_LDA(dst, b, h) do { _Pragma("unroll") for (int m = 0; m < 4; ++m) _Pragma("unroll") for (int k = 0; k < 2; ++k) dst[m][k] = *(const LAS bf16x8*)(lds + PG8_SA(b, h) + aoff + m * 2048 + k * 1024); } while (0)
; #define PG8_LDB(dst, b, h) do { _Pragma("unroll") for (int n = 0; n < 2; ++n) _Pragma("unroll") for (int k = 0; k < 2; ++k) dst[n][k] = *(const LAS bf16x8*)(lds + PG8_SB(b, h) + boff + n * 2048 + k * 1024); } while (0)
; #define PG8_WAIT_V(n) asm volatile("s_waitcnt vmcnt(" #n ")" ::: "memory")
; template <class Sched, class Epi>
; __device__ __forceinline__ void gemm_run(LAS unsigned char* lds, const Sched& S, const Epi& E) {
;     ...
;     f32x4 acc[2][2][4][2];
; #pragma unroll
;     for (int a = 0; a < 2; ++a)
; #pragma unroll
;         for (int b = 0; b < 2; ++b)
; #pragma unroll
;             for (int m = 0; m < 4; ++m)
; #pragma unroll
;                 for (int n = 0; n < 2; ++n) acc[a][b][m][n] = (f32x4){0.f, 0.f, 0.f, 0.f};
;     ...
;     for (;;) {
;         const bool has_next = S.next(ui + 1, nxt);
;         const char* nA = has_next ? nxt.A : cA; const char* nB = has_next ? nxt.B : cB; const unsigned nlda = has_next ? nxt.lda : lda, nldb = has_next ? nxt.ldb : ldb;
;         const int nt = cur.nt;
;         for (int t = 0; t < nt; t += 2) {
;             const bool last = (t == nt - 2);
;             const char* a1 = cA + (size_t)(t + 1) * kstep;
;             const char* a2 = last ? nA : cA + (size_t)(t + 2) * kstep; const char* b2 = last ? nB : cB + (size_t)(t + 2) * kstep;
;             const unsigned la2 = last ? nlda : lda, lb2 = last ? nldb : ldb;
;             const char* a3 = a2 + kstep; const char* b3 = b2 + kstep;
;             PG8_LDB(B0, 0, 0); PG8_LDB(B1, 0, 1); PG8_SCHED; PG8_LDA(At, 0, 0); PG8_STAGE(PG8_SA(1, 1), a1 + (size_t)HALF * lda, RA, lda);
;             PG8_WAIT_V(8); PG8_WAIT_L(0); PG8_BAR; PG8_MMA(0, 0, At, B0); PG8_MMA(0, 1, At, B1); PG8_BAR; PG8_SCHED;
;             PG8_LDA(At, 0, 1); PG8_STAGE(PG8_SB(0, 0), b2, RB, lb2); PG8_STAGE(PG8_SB(0, 1), b2 + (size_t)HALF * lb2, RB, lb2); PG8_STAGE(PG8_SA(0, 0), a2, RA, la2);
.LBB0_699:
	s_add_u32 s38, s20, 0x100
	s_addc_u32 s39, s21, 0
	v_lshl_add_u64 v[146:147], s[18:19], 0, v[142:143]
	v_lshl_add_u64 v[148:149], s[18:19], 0, v[144:145]
	s_mov_b32 s40, -2
	s_mov_b64 s[20:21], 0
	ds_read_b128 v[166:169], v160
	ds_read_b128 v[170:173], v160 offset:1024
	ds_read_b128 v[174:177], v160 offset:2048
	ds_read_b128 v[178:181], v160 offset:3072
	ds_read_b128 v[182:185], v161
	ds_read_b128 v[186:189], v161 offset:1024
	ds_read_b128 v[190:193], v161 offset:2048
	ds_read_b128 v[194:197], v161 offset:3072
	s_add_u32 s22, s18, s20
	s_addc_u32 s23, s19, s21
	s_add_u32 s22, s22, 0x100
	s_addc_u32 s23, s23, 0
	s_add_u32 s41, s38, s20
	s_addc_u32 s42, s39, s21
	s_cmpk_eq_i32 s20, 0x200
	s_cselect_b32 s29, s13, s23
	s_cselect_b32 s28, s12, s22
	s_cselect_b32 s23, s15, s42
	s_cselect_b32 s22, s14, s41
	s_mov_b32 m0, s58
	v_lshl_add_u64 v[230:231], v[146:147], 0, s[20:21]
	ds_read_b128 v[198:201], v162
	ds_read_b128 v[202:205], v162 offset:1024
	ds_read_b128 v[206:209], v162 offset:2048
	ds_read_b128 v[210:213], v162 offset:3072
	ds_read_b128 v[214:217], v162 offset:4096
	ds_read_b128 v[218:221], v162 offset:5120
	ds_read_b128 v[222:225], v162 offset:6144
	ds_read_b128 v[226:229], v162 offset:7168
	global_load_lds_dwordx4 v[230:231], off
	v_lshl_add_u64 v[230:231], v[148:149], 0, s[20:21]
	s_mov_b32 m0, s59
	s_nop 0
	global_load_lds_dwordx4 v[230:231], off
	s_waitcnt vmcnt(8)
	s_waitcnt lgkmcnt(0)
	s_barrier
	s_waitcnt lgkmcnt(0)
	v_mfma_f32_16x16x32_bf16 v[126:129], v[166:169], v[198:201], 0
	v_mfma_f32_16x16x32_bf16 v[122:125], v[174:177], v[198:201], 0
	v_mfma_f32_16x16x32_bf16 v[110:113], v[166:169], v[206:209], 0
	v_mfma_f32_16x16x32_bf16 v[106:109], v[174:177], v[206:209], 0
	v_mfma_f32_16x16x32_bf16 v[94:97], v[166:169], v[214:217], 0
	v_mfma_f32_16x16x32_bf16 v[90:93], v[174:177], v[214:217], 0
	v_mfma_f32_16x16x32_bf16 v[78:81], v[166:169], v[222:225], 0
	v_mfma_f32_16x16x32_bf16 v[74:77], v[174:177], v[222:225], 0
	v_mfma_f32_16x16x32_bf16 v[126:129], v[170:173], v[202:205], v[126:129]
	v_mfma_f32_16x16x32_bf16 v[122:125], v[178:181], v[202:205], v[122:125]
	v_mfma_f32_16x16x32_bf16 v[110:113], v[170:173], v[210:213], v[110:113]
	v_mfma_f32_16x16x32_bf16 v[106:109], v[178:181], v[210:213], v[106:109]
	v_mfma_f32_16x16x32_bf16 v[94:97], v[170:173], v[218:221], v[94:97]
	v_mfma_f32_16x16x32_bf16 v[90:93], v[178:181], v[218:221], v[90:93]
	v_mfma_f32_16x16x32_bf16 v[78:81], v[170:173], v[226:229], v[78:81]
	v_mfma_f32_16x16x32_bf16 v[74:77], v[178:181], v[226:229], v[74:77]
	v_mfma_f32_16x16x32_bf16 v[118:121], v[182:185], v[198:201], 0
	v_mfma_f32_16x16x32_bf16 v[114:117], v[190:193], v[198:201], 0
	v_mfma_f32_16x16x32_bf16 v[102:105], v[182:185], v[206:209], 0
	v_mfma_f32_16x16x32_bf16 v[98:101], v[190:193], v[206:209], 0
	v_mfma_f32_16x16x32_bf16 v[86:89], v[182:185], v[214:217], 0
	v_mfma_f32_16x16x32_bf16 v[82:85], v[190:193], v[214:217], 0
	v_mfma_f32_16x16x32_bf16 v[70:73], v[182:185], v[222:225], 0
	v_mfma_f32_16x16x32_bf16 v[66:69], v[190:193], v[222:225], 0
	v_mfma_f32_16x16x32_bf16 v[118:121], v[186:189], v[202:205], v[118:121]
	v_mfma_f32_16x16x32_bf16 v[114:117], v[194:197], v[202:205], v[114:117]
	v_mfma_f32_16x16x32_bf16 v[102:105], v[186:189], v[210:213], v[102:105]
	v_mfma_f32_16x16x32_bf16 v[98:101], v[194:197], v[210:213], v[98:101]
	v_mfma_f32_16x16x32_bf16 v[86:89], v[186:189], v[218:221], v[86:89]
	v_mfma_f32_16x16x32_bf16 v[82:85], v[194:197], v[218:221], v[82:85]
	v_mfma_f32_16x16x32_bf16 v[70:73], v[186:189], v[226:229], v[70:73]
	v_mfma_f32_16x16x32_bf16 v[66:69], v[194:197], v[226:229], v[66:69]
	s_barrier
	v_lshl_add_u64 v[230:231], s[22:23], 0, v[132:133]
	s_add_u32 s42, s22, 0x18000
	s_mov_b32 m0, s60
	v_lshl_add_u64 v[230:231], v[230:231], 0, v[130:131]
	v_lshl_add_u64 v[232:233], s[22:23], 0, v[136:137]
	s_addc_u32 s43, s23, 0
	ds_read_b128 v[198:201], v162 offset:16384
	ds_read_b128 v[202:205], v162 offset:17408
	ds_read_b128 v[206:209], v162 offset:18432
	ds_read_b128 v[210:213], v162 offset:19456
	ds_read_b128 v[214:217], v162 offset:20480
	ds_read_b128 v[218:221], v162 offset:21504
	ds_read_b128 v[222:225], v162 offset:22528
	ds_read_b128 v[226:229], v162 offset:23552
	global_load_lds_dwordx4 v[230:231], off
	v_lshl_add_u64 v[232:233], v[232:233], 0, v[130:131]
	s_mov_b32 m0, s61
	v_lshl_add_u64 v[234:235], s[42:43], 0, v[132:133]
	global_load_lds_dwordx4 v[232:233], off
	v_lshl_add_u64 v[234:235], v[234:235], 0, v[130:131]
	s_mov_b32 m0, s62
	v_lshl_add_u64 v[236:237], s[28:29], 0, v[140:141]
	global_load_lds_dwordx4 v[234:235], off
	v_lshl_add_u64 v[234:235], s[42:43], 0, v[136:137]
	v_lshl_add_u64 v[234:235], v[234:235], 0, v[130:131]
	s_mov_b32 m0, s63
	v_lshl_add_u64 v[236:237], v[236:237], 0, v[130:131]
	global_load_lds_dwordx4 v[234:235], off
	v_lshl_add_u64 v[234:235], s[28:29], 0, v[138:139]
	v_lshl_add_u64 v[234:235], v[234:235], 0, v[130:131]
	s_mov_b32 m0, s35
	s_nop 0
	global_load_lds_dwordx4 v[234:235], off
	s_mov_b32 m0, s36
	s_nop 0
	global_load_lds_dwordx4 v[236:237], off
	s_waitcnt vmcnt(8)
	s_waitcnt lgkmcnt(0)
	s_barrier
; #define PG8_STAGE(bufoff, gbase, RR, ld) do { _Pragma("unroll") for (int _i = 0; _i < 2; ++_i) \
;         __builtin_amdgcn_global_load_lds((const unsigned*)((const char*)(gbase) + (RR)[_i] * (ld) + C2[_i]), (LAS unsigned*)(lds + (bufoff) + ldsw + _i * 8192), 16, 0, 0); } while (0)
; #define PG8_LDA(dst, b, h) do { _Pragma("unroll") for (int m = 0; m < 4; ++m) _Pragma("unroll") for (int k = 0; k < 2; ++k) dst[m][k] = *(const LAS bf16x8*)(lds + PG8_SA(b, h) + aoff + m * 2048 + k * 1024); } while (0)
; #define PG8_LDB(dst, b, h) do { _Pragma("unroll") for (int n = 0; n < 2; ++n) _Pragma("unroll") for (int k = 0; k < 2; ++k) dst[n][k] = *(const LAS bf16x8*)(lds + PG8_SB(b, h) + boff + n * 2048 + k * 1024); } while (0)
; #define PG8_MMA(ai, bj, At, Bt) do { __builtin_amdgcn_s_setprio(1); _Pragma("unroll") for (int m = 0; m < 4; ++m) _Pragma("unroll") for (int n = 0; n < 2; ++n) _Pragma("unroll") for (int k = 0; k < 2; ++k) \
;         acc[ai][bj][m][n] = __builtin_amdgcn_mfma_f32_16x16x32_bf16(Bt[n][k], At[m][k], acc[ai][bj][m][n], 0, 0, 0); __builtin_amdgcn_s_setprio(0); } while (0)
; #define PG8_WAIT_V(n) asm volatile("s_waitcnt vmcnt(" #n ")" ::: "memory")
; #define PG8_WAIT_L(n) asm volatile("s_waitcnt lgkmcnt(" #n ")" ::: "memory")
; #define PG8_BAR __builtin_amdgcn_s_barrier()
; #define PG8_SCHED __builtin_amdgcn_sched_barrier(0)
; template <class Sched, class Epi>
; __device__ __forceinline__ void gemm_run(LAS unsigned char* lds, const Sched& S, const Epi& E) {
;     ...
;             PG8_WAIT_V(8); PG8_WAIT_L(0); PG8_BAR; PG8_MMA(1, 0, At, B0); PG8_MMA(1, 1, At, B1); PG8_BAR; PG8_SCHED;
;             PG8_LDB(B0, 1, 0); PG8_LDB(B1, 1, 1); PG8_SCHED; PG8_LDA(At, 1, 0); PG8_STAGE(PG8_SA(0, 1), a2 + (size_t)HALF * la2, RA, la2);
;             PG8_WAIT_V(8); PG8_WAIT_L(0); PG8_BAR; PG8_MMA(0, 0, At, B0); PG8_MMA(0, 1, At, B1); PG8_BAR; PG8_SCHED;
	s_waitcnt lgkmcnt(0)
	v_mfma_f32_16x16x32_bf16 v[62:65], v[166:169], v[198:201], 0
	v_mfma_f32_16x16x32_bf16 v[58:61], v[174:177], v[198:201], 0
	v_mfma_f32_16x16x32_bf16 v[46:49], v[166:169], v[206:209], 0
	v_mfma_f32_16x16x32_bf16 v[42:45], v[174:177], v[206:209], 0
	v_mfma_f32_16x16x32_bf16 v[30:33], v[166:169], v[214:217], 0
	v_mfma_f32_16x16x32_bf16 v[26:29], v[174:177], v[214:217], 0
	v_mfma_f32_16x16x32_bf16 v[14:17], v[166:169], v[222:225], 0
	v_mfma_f32_16x16x32_bf16 v[10:13], v[174:177], v[222:225], 0
	v_mfma_f32_16x16x32_bf16 v[62:65], v[170:173], v[202:205], v[62:65]
	v_mfma_f32_16x16x32_bf16 v[58:61], v[178:181], v[202:205], v[58:61]
	v_mfma_f32_16x16x32_bf16 v[46:49], v[170:173], v[210:213], v[46:49]
	v_mfma_f32_16x16x32_bf16 v[42:45], v[178:181], v[210:213], v[42:45]
	v_mfma_f32_16x16x32_bf16 v[30:33], v[170:173], v[218:221], v[30:33]
	v_mfma_f32_16x16x32_bf16 v[26:29], v[178:181], v[218:221], v[26:29]
	v_mfma_f32_16x16x32_bf16 v[14:17], v[170:173], v[226:229], v[14:17]
	v_mfma_f32_16x16x32_bf16 v[10:13], v[178:181], v[226:229], v[10:13]
	v_mfma_f32_16x16x32_bf16 v[54:57], v[182:185], v[198:201], 0
	v_mfma_f32_16x16x32_bf16 v[50:53], v[190:193], v[198:201], 0
	v_mfma_f32_16x16x32_bf16 v[38:41], v[182:185], v[206:209], 0
	v_mfma_f32_16x16x32_bf16 v[34:37], v[190:193], v[206:209], 0
	v_mfma_f32_16x16x32_bf16 v[22:25], v[182:185], v[214:217], 0
	v_mfma_f32_16x16x32_bf16 v[18:21], v[190:193], v[214:217], 0
	v_mfma_f32_16x16x32_bf16 v[6:9], v[182:185], v[222:225], 0
	v_mfma_f32_16x16x32_bf16 v[2:5], v[190:193], v[222:225], 0
	v_mfma_f32_16x16x32_bf16 v[54:57], v[186:189], v[202:205], v[54:57]
	v_mfma_f32_16x16x32_bf16 v[50:53], v[194:197], v[202:205], v[50:53]
	v_mfma_f32_16x16x32_bf16 v[38:41], v[186:189], v[210:213], v[38:41]
	v_mfma_f32_16x16x32_bf16 v[34:37], v[194:197], v[210:213], v[34:37]
	v_mfma_f32_16x16x32_bf16 v[22:25], v[186:189], v[218:221], v[22:25]
	v_mfma_f32_16x16x32_bf16 v[18:21], v[194:197], v[218:221], v[18:21]
	v_mfma_f32_16x16x32_bf16 v[6:9], v[186:189], v[226:229], v[6:9]
	v_mfma_f32_16x16x32_bf16 v[2:5], v[194:197], v[226:229], v[2:5]
	s_barrier
	ds_read_b128 v[166:169], v163
	ds_read_b128 v[170:173], v163 offset:1024
	ds_read_b128 v[174:177], v163 offset:2048
	ds_read_b128 v[178:181], v163 offset:3072
	ds_read_b128 v[182:185], v164
	ds_read_b128 v[186:189], v164 offset:1024
	ds_read_b128 v[190:193], v164 offset:2048
	ds_read_b128 v[194:197], v164 offset:3072
	s_add_u32 s28, s28, 0x18000
	s_addc_u32 s29, s29, 0
	v_lshl_add_u64 v[238:239], s[28:29], 0, v[138:139]
	s_mov_b32 m0, s37
	v_lshl_add_u64 v[238:239], v[238:239], 0, v[130:131]
	ds_read_b128 v[198:201], v162 offset:32768
	ds_read_b128 v[202:205], v162 offset:33792
	ds_read_b128 v[206:209], v162 offset:34816
	ds_read_b128 v[210:213], v162 offset:35840
	ds_read_b128 v[214:217], v162 offset:36864
	ds_read_b128 v[218:221], v162 offset:37888
	ds_read_b128 v[222:225], v162 offset:38912
	ds_read_b128 v[226:229], v162 offset:39936
	global_load_lds_dwordx4 v[238:239], off
	v_lshl_add_u64 v[238:239], s[28:29], 0, v[140:141]
	v_lshl_add_u64 v[238:239], v[238:239], 0, v[130:131]
	s_mov_b32 m0, s54
	s_nop 0
	global_load_lds_dwordx4 v[238:239], off
	s_waitcnt vmcnt(8)
	s_waitcnt lgkmcnt(0)
	s_barrier
	s_waitcnt lgkmcnt(0)
	v_mfma_f32_16x16x32_bf16 v[126:129], v[166:169], v[198:201], v[126:129]
	v_mfma_f32_16x16x32_bf16 v[122:125], v[174:177], v[198:201], v[122:125]
	v_mfma_f32_16x16x32_bf16 v[110:113], v[166:169], v[206:209], v[110:113]
	v_mfma_f32_16x16x32_bf16 v[106:109], v[174:177], v[206:209], v[106:109]
	v_mfma_f32_16x16x32_bf16 v[94:97], v[166:169], v[214:217], v[94:97]
	v_mfma_f32_16x16x32_bf16 v[90:93], v[174:177], v[214:217], v[90:93]
	v_mfma_f32_16x16x32_bf16 v[78:81], v[166:169], v[222:225], v[78:81]
	v_mfma_f32_16x16x32_bf16 v[74:77], v[174:177], v[222:225], v[74:77]
	v_mfma_f32_16x16x32_bf16 v[126:129], v[170:173], v[202:205], v[126:129]
	v_mfma_f32_16x16x32_bf16 v[122:125], v[178:181], v[202:205], v[122:125]
	v_mfma_f32_16x16x32_bf16 v[110:113], v[170:173], v[210:213], v[110:113]
	v_mfma_f32_16x16x32_bf16 v[106:109], v[178:181], v[210:213], v[106:109]
	v_mfma_f32_16x16x32_bf16 v[94:97], v[170:173], v[218:221], v[94:97]
	v_mfma_f32_16x16x32_bf16 v[90:93], v[178:181], v[218:221], v[90:93]
	v_mfma_f32_16x16x32_bf16 v[78:81], v[170:173], v[226:229], v[78:81]
	v_mfma_f32_16x16x32_bf16 v[74:77], v[178:181], v[226:229], v[74:77]
	v_mfma_f32_16x16x32_bf16 v[118:121], v[182:185], v[198:201], v[118:121]
	v_mfma_f32_16x16x32_bf16 v[114:117], v[190:193], v[198:201], v[114:117]
	v_mfma_f32_16x16x32_bf16 v[102:105], v[182:185], v[206:209], v[102:105]
	v_mfma_f32_16x16x32_bf16 v[98:101], v[190:193], v[206:209], v[98:101]
	v_mfma_f32_16x16x32_bf16 v[86:89], v[182:185], v[214:217], v[86:89]
	v_mfma_f32_16x16x32_bf16 v[82:85], v[190:193], v[214:217], v[82:85]
	v_mfma_f32_16x16x32_bf16 v[70:73], v[182:185], v[222:225], v[70:73]
	v_mfma_f32_16x16x32_bf16 v[66:69], v[190:193], v[222:225], v[66:69]
	v_mfma_f32_16x16x32_bf16 v[118:121], v[186:189], v[202:205], v[118:121]
	v_mfma_f32_16x16x32_bf16 v[114:117], v[194:197], v[202:205], v[114:117]
	v_mfma_f32_16x16x32_bf16 v[102:105], v[186:189], v[210:213], v[102:105]
	v_mfma_f32_16x16x32_bf16 v[98:101], v[194:197], v[210:213], v[98:101]
	v_mfma_f32_16x16x32_bf16 v[86:89], v[186:189], v[218:221], v[86:89]
	v_mfma_f32_16x16x32_bf16 v[82:85], v[194:197], v[218:221], v[82:85]
	v_mfma_f32_16x16x32_bf16 v[70:73], v[186:189], v[226:229], v[70:73]
	v_mfma_f32_16x16x32_bf16 v[66:69], v[194:197], v[226:229], v[66:69]
	s_barrier
; #define PG8_STAGE(bufoff, gbase, RR, ld) do { _Pragma("unroll") for (int _i = 0; _i < 2; ++_i) \
;         __builtin_amdgcn_global_load_lds((const unsigned*)((const char*)(gbase) + (RR)[_i] * (ld) + C2[_i]), (LAS unsigned*)(lds + (bufoff) + ldsw + _i * 8192), 16, 0, 0); } while (0)
; #define PG8_LDA(dst, b, h) do { _Pragma("unroll") for (int m = 0; m < 4; ++m) _Pragma("unroll") for (int k = 0; k < 2; ++k) dst[m][k] = *(const LAS bf16x8*)(lds + PG8_SA(b, h) + aoff + m * 2048 + k * 1024); } while (0)
; #define PG8_MMA(ai, bj, At, Bt) do { __builtin_amdgcn_s_setprio(1); _Pragma("unroll") for (int m = 0; m < 4; ++m) _Pragma("unroll") for (int n = 0; n < 2; ++n) _Pragma("unroll") for (int k = 0; k < 2; ++k) \
;         acc[ai][bj][m][n] = __builtin_amdgcn_mfma_f32_16x16x32_bf16(Bt[n][k], At[m][k], acc[ai][bj][m][n], 0, 0, 0); __builtin_amdgcn_s_setprio(0); } while (0)
; #define PG8_WAIT_V(n) asm volatile("s_waitcnt vmcnt(" #n ")" ::: "memory")
; #define PG8_WAIT_L(n) asm volatile("s_waitcnt lgkmcnt(" #n ")" ::: "memory")
; #define PG8_BAR __builtin_amdgcn_s_barrier()
; #define PG8_SCHED __builtin_amdgcn_sched_barrier(0)
; template <class Sched, class Epi>
; __device__ __forceinline__ void gemm_run(LAS unsigned char* lds, const Sched& S, const Epi& E) {
;     ...
;             PG8_LDA(At, 1, 1); PG8_STAGE(PG8_SB(1, 0), b3, RB, lb2); PG8_STAGE(PG8_SB(1, 1), b3 + (size_t)HALF * lb2, RB, lb2); PG8_STAGE(PG8_SA(1, 0), a3, RA, la2);
;             PG8_WAIT_V(8); PG8_WAIT_L(0); PG8_BAR; PG8_MMA(1, 0, At, B0); PG8_MMA(1, 1, At, B1); PG8_BAR; PG8_SCHED;
;         }
	s_mov_b32 m0, s64
	v_lshl_add_u64 v[230:231], v[230:231], 0, s[6:7]
	s_add_u32 s22, s22, 0x18080
	ds_read_b128 v[198:201], v162 offset:49152
	ds_read_b128 v[202:205], v162 offset:50176
	ds_read_b128 v[206:209], v162 offset:51200
	ds_read_b128 v[210:213], v162 offset:52224
	ds_read_b128 v[214:217], v162 offset:53248
	ds_read_b128 v[218:221], v162 offset:54272
	ds_read_b128 v[222:225], v162 offset:55296
	ds_read_b128 v[226:229], v162 offset:56320
	global_load_lds_dwordx4 v[230:231], off
	v_lshl_add_u64 v[230:231], v[232:233], 0, s[6:7]
	s_mov_b32 m0, s65
	s_addc_u32 s23, s23, 0
	global_load_lds_dwordx4 v[230:231], off
	v_lshl_add_u64 v[230:231], s[22:23], 0, v[132:133]
	v_lshl_add_u64 v[230:231], v[230:231], 0, v[130:131]
	s_mov_b32 m0, s66
	s_nop 0
	global_load_lds_dwordx4 v[230:231], off
	v_lshl_add_u64 v[230:231], s[22:23], 0, v[136:137]
	v_lshl_add_u64 v[230:231], v[230:231], 0, v[130:131]
	s_mov_b32 m0, s67
	s_nop 0
	global_load_lds_dwordx4 v[230:231], off
	v_lshl_add_u64 v[230:231], v[234:235], 0, s[6:7]
	s_mov_b32 m0, s56
	s_nop 0
	global_load_lds_dwordx4 v[230:231], off
	v_lshl_add_u64 v[230:231], v[236:237], 0, s[6:7]
	s_mov_b32 m0, s57
	s_nop 0
	global_load_lds_dwordx4 v[230:231], off
	s_waitcnt vmcnt(8)
	s_waitcnt lgkmcnt(0)
	s_barrier
	s_waitcnt lgkmcnt(0)
	v_mfma_f32_16x16x32_bf16 v[62:65], v[166:169], v[198:201], v[62:65]
	v_mfma_f32_16x16x32_bf16 v[58:61], v[174:177], v[198:201], v[58:61]
	v_mfma_f32_16x16x32_bf16 v[46:49], v[166:169], v[206:209], v[46:49]
	v_mfma_f32_16x16x32_bf16 v[42:45], v[174:177], v[206:209], v[42:45]
	v_mfma_f32_16x16x32_bf16 v[30:33], v[166:169], v[214:217], v[30:33]
	v_mfma_f32_16x16x32_bf16 v[26:29], v[174:177], v[214:217], v[26:29]
	v_mfma_f32_16x16x32_bf16 v[14:17], v[166:169], v[222:225], v[14:17]
	v_mfma_f32_16x16x32_bf16 v[10:13], v[174:177], v[222:225], v[10:13]
	v_mfma_f32_16x16x32_bf16 v[62:65], v[170:173], v[202:205], v[62:65]
	v_mfma_f32_16x16x32_bf16 v[58:61], v[178:181], v[202:205], v[58:61]
	v_mfma_f32_16x16x32_bf16 v[46:49], v[170:173], v[210:213], v[46:49]
	v_mfma_f32_16x16x32_bf16 v[42:45], v[178:181], v[210:213], v[42:45]
	v_mfma_f32_16x16x32_bf16 v[30:33], v[170:173], v[218:221], v[30:33]
	v_mfma_f32_16x16x32_bf16 v[26:29], v[178:181], v[218:221], v[26:29]
	v_mfma_f32_16x16x32_bf16 v[14:17], v[170:173], v[226:229], v[14:17]
	v_mfma_f32_16x16x32_bf16 v[10:13], v[178:181], v[226:229], v[10:13]
	v_mfma_f32_16x16x32_bf16 v[54:57], v[182:185], v[198:201], v[54:57]
	v_mfma_f32_16x16x32_bf16 v[50:53], v[190:193], v[198:201], v[50:53]
	v_mfma_f32_16x16x32_bf16 v[38:41], v[182:185], v[206:209], v[38:41]
	v_mfma_f32_16x16x32_bf16 v[34:37], v[190:193], v[206:209], v[34:37]
	v_mfma_f32_16x16x32_bf16 v[22:25], v[182:185], v[214:217], v[22:25]
	v_mfma_f32_16x16x32_bf16 v[18:21], v[190:193], v[214:217], v[18:21]
	v_mfma_f32_16x16x32_bf16 v[6:9], v[182:185], v[222:225], v[6:9]
	v_mfma_f32_16x16x32_bf16 v[2:5], v[190:193], v[222:225], v[2:5]
	v_mfma_f32_16x16x32_bf16 v[54:57], v[186:189], v[202:205], v[54:57]
	v_mfma_f32_16x16x32_bf16 v[50:53], v[194:197], v[202:205], v[50:53]
	v_mfma_f32_16x16x32_bf16 v[38:41], v[186:189], v[210:213], v[38:41]
	v_mfma_f32_16x16x32_bf16 v[34:37], v[194:197], v[210:213], v[34:37]
	v_mfma_f32_16x16x32_bf16 v[22:25], v[186:189], v[218:221], v[22:25]
	v_mfma_f32_16x16x32_bf16 v[18:21], v[194:197], v[218:221], v[18:21]
	v_mfma_f32_16x16x32_bf16 v[6:9], v[186:189], v[226:229], v[6:9]
	v_mfma_f32_16x16x32_bf16 v[2:5], v[194:197], v[226:229], v[2:5]
	s_barrier
	s_add_i32 s40, s40, 2
	s_add_u32 s20, s20, 0x100
	s_addc_u32 s21, s21, 0
	s_cmp_gt_u32 s40, 3
	s_cbranch_scc0 .LBB0_700
	.p2align 6

; #define PG8_STAGE(bufoff, gbase, RR, ld) do { _Pragma("unroll") for (int _i = 0; _i < 2; ++_i) \
;         __builtin_amdgcn_global_load_lds((const unsigned*)((const char*)(gbase) + (RR)[_i] * (ld) + C2[_i]), (LAS unsigned*)(lds + (bufoff) + ldsw + _i * 8192), 16, 0, 0); } while (0)
; #define PG8_LDA(dst, b, h) do { _Pragma("unroll") for (int m = 0; m < 4; ++m) _Pragma("unroll") for (int k = 0; k < 2; ++k) dst[m][k] = *(const LAS bf16x8*)(lds + PG8_SA(b, h) + aoff + m * 2048 + k * 1024); } while (0)
; #define PG8_LDB(dst, b, h) do { _Pragma("unroll") for (int n = 0; n < 2; ++n) _Pragma("unroll") for (int k = 0; k < 2; ++k) dst[n][k] = *(const LAS bf16x8*)(lds + PG8_SB(b, h) + boff + n * 2048 + k * 1024); } while (0)
; #define PG8_WAIT_V(n) asm volatile("s_waitcnt vmcnt(" #n ")" ::: "memory")
; template <class Sched, class Epi>
; __device__ __forceinline__ void gemm_run(LAS unsigned char* lds, const Sched& S, const Epi& E) {
;     ...
;     f32x4 acc[2][2][4][2];
; #pragma unroll
;     for (int a = 0; a < 2; ++a)
; #pragma unroll
;         for (int b = 0; b < 2; ++b)
; #pragma unroll
;             for (int m = 0; m < 4; ++m)
; #pragma unroll
;                 for (int n = 0; n < 2; ++n) acc[a][b][m][n] = (f32x4){0.f, 0.f, 0.f, 0.f};
;     ...
;     for (;;) {
;         const bool has_next = S.next(ui + 1, nxt);
;         const char* nA = has_next ? nxt.A : cA; const char* nB = has_next ? nxt.B : cB; const unsigned nlda = has_next ? nxt.lda : lda, nldb = has_next ? nxt.ldb : ldb;
;         const int nt = cur.nt;
;         for (int t = 0; t < nt; t += 2) {
;             const bool last = (t == nt - 2);
;             const char* a1 = cA + (size_t)(t + 1) * kstep;
;             const char* a2 = last ? nA : cA + (size_t)(t + 2) * kstep; const char* b2 = last ? nB : cB + (size_t)(t + 2) * kstep;
;             const unsigned la2 = last ? nlda : lda, lb2 = last ? nldb : ldb;
;             const char* a3 = a2 + kstep; const char* b3 = b2 + kstep;
;             PG8_LDB(B0, 0, 0); PG8_LDB(B1, 0, 1); PG8_SCHED; PG8_LDA(At, 0, 0); PG8_STAGE(PG8_SA(1, 1), a1 + (size_t)HALF * lda, RA, lda);
;             PG8_WAIT_V(8); PG8_WAIT_L(0); PG8_BAR; PG8_MMA(0, 0, At, B0); PG8_MMA(0, 1, At, B1); PG8_BAR; PG8_SCHED;
;             PG8_LDA(At, 0, 1); PG8_STAGE(PG8_SB(0, 0), b2, RB, lb2); PG8_STAGE(PG8_SB(0, 1), b2 + (size_t)HALF * lb2, RB, lb2); PG8_STAGE(PG8_SA(0, 0), a2, RA, la2);
.LBB0_805:
	s_mov_b32 s57, s7
	s_lshl_b64 s[48:49], s[56:57], 7
	v_mul_lo_u32 v148, v191, s56
	v_lshl_add_u64 v[2:3], s[54:55], 0, v[150:151]
	v_lshl_add_u64 v[4:5], s[48:49], 0, v[148:149]
	v_mul_lo_u32 v148, v192, s56
	s_add_i32 s44, s81, -2
	v_lshl_add_u64 v[130:131], v[2:3], 0, v[4:5]
	v_lshl_add_u64 v[4:5], s[48:49], 0, v[148:149]
	s_add_u32 s45, s58, 0x100
	v_lshl_add_u64 v[132:133], v[2:3], 0, v[4:5]
	s_addc_u32 s46, s59, 0
	s_mov_b32 s6, 0
	s_mov_b64 s[58:59], 0
	ds_read_b128 v[134:137], v193
	ds_read_b128 v[138:141], v193 offset:1024
	ds_read_b128 v[142:145], v193 offset:2048
	ds_read_b128 v[152:155], v193 offset:3072
	ds_read_b128 v[156:159], v194
	ds_read_b128 v[160:163], v194 offset:1024
	ds_read_b128 v[164:167], v194 offset:2048
	ds_read_b128 v[168:171], v194 offset:3072
	s_add_i32 s47, s6, 2
	s_add_u32 s48, s54, s58
	s_addc_u32 s49, s55, s59
	s_add_u32 s48, s48, 0x100
	s_addc_u32 s49, s49, 0
	s_add_u32 s50, s45, s58
	s_addc_u32 s51, s46, s59
	s_cmp_eq_u32 s44, s6
	s_cselect_b32 s6, s39, s82
	s_cselect_b32 s61, s31, s49
	s_cselect_b32 s60, s30, s48
	s_cselect_b32 s62, s80, s56
	s_cselect_b32 s49, s41, s51
	s_cselect_b32 s48, s40, s50
	v_lshl_add_u64 v[216:217], v[130:131], 0, s[58:59]
	s_add_i32 m0, s43, 0xc000
	ds_read_b128 v[172:175], v195
	ds_read_b128 v[176:179], v195 offset:1024
	ds_read_b128 v[180:183], v195 offset:2048
	ds_read_b128 v[196:199], v195 offset:3072
	ds_read_b128 v[200:203], v195 offset:4096
	ds_read_b128 v[204:207], v195 offset:5120
	ds_read_b128 v[208:211], v195 offset:6144
	ds_read_b128 v[212:215], v195 offset:7168
	global_load_lds_dwordx4 v[216:217], off
	v_lshl_add_u64 v[216:217], v[132:133], 0, s[58:59]
	s_add_i32 m0, s43, 0xe000
	s_nop 0
	global_load_lds_dwordx4 v[216:217], off
	s_waitcnt vmcnt(8)
	s_waitcnt lgkmcnt(0)
	s_barrier
	s_waitcnt lgkmcnt(0)
	v_mfma_f32_16x16x32_bf16 v[126:129], v[134:137], v[172:175], 0
	v_mfma_f32_16x16x32_bf16 v[118:121], v[142:145], v[172:175], 0
	v_mfma_f32_16x16x32_bf16 v[110:113], v[134:137], v[180:183], 0
	v_mfma_f32_16x16x32_bf16 v[102:105], v[142:145], v[180:183], 0
	v_mfma_f32_16x16x32_bf16 v[94:97], v[134:137], v[200:203], 0
	v_mfma_f32_16x16x32_bf16 v[86:89], v[142:145], v[200:203], 0
	v_mfma_f32_16x16x32_bf16 v[78:81], v[134:137], v[208:211], 0
	v_mfma_f32_16x16x32_bf16 v[70:73], v[142:145], v[208:211], 0
	v_mfma_f32_16x16x32_bf16 v[126:129], v[138:141], v[176:179], v[126:129]
	v_mfma_f32_16x16x32_bf16 v[118:121], v[152:155], v[176:179], v[118:121]
	v_mfma_f32_16x16x32_bf16 v[110:113], v[138:141], v[196:199], v[110:113]
	v_mfma_f32_16x16x32_bf16 v[102:105], v[152:155], v[196:199], v[102:105]
	v_mfma_f32_16x16x32_bf16 v[94:97], v[138:141], v[204:207], v[94:97]
	v_mfma_f32_16x16x32_bf16 v[86:89], v[152:155], v[204:207], v[86:89]
	v_mfma_f32_16x16x32_bf16 v[78:81], v[138:141], v[212:215], v[78:81]
	v_mfma_f32_16x16x32_bf16 v[70:73], v[152:155], v[212:215], v[70:73]
	v_mfma_f32_16x16x32_bf16 v[122:125], v[156:159], v[172:175], 0
	v_mfma_f32_16x16x32_bf16 v[114:117], v[164:167], v[172:175], 0
	v_mfma_f32_16x16x32_bf16 v[106:109], v[156:159], v[180:183], 0
	v_mfma_f32_16x16x32_bf16 v[98:101], v[164:167], v[180:183], 0
	v_mfma_f32_16x16x32_bf16 v[90:93], v[156:159], v[200:203], 0
	v_mfma_f32_16x16x32_bf16 v[82:85], v[164:167], v[200:203], 0
	v_mfma_f32_16x16x32_bf16 v[74:77], v[156:159], v[208:211], 0
	v_mfma_f32_16x16x32_bf16 v[66:69], v[164:167], v[208:211], 0
	v_mfma_f32_16x16x32_bf16 v[122:125], v[160:163], v[176:179], v[122:125]
	v_mfma_f32_16x16x32_bf16 v[114:117], v[168:171], v[176:179], v[114:117]
	v_mfma_f32_16x16x32_bf16 v[106:109], v[160:163], v[196:199], v[106:109]
	v_mfma_f32_16x16x32_bf16 v[98:101], v[168:171], v[196:199], v[98:101]
	v_mfma_f32_16x16x32_bf16 v[90:93], v[160:163], v[204:207], v[90:93]
	v_mfma_f32_16x16x32_bf16 v[82:85], v[168:171], v[204:207], v[82:85]
	v_mfma_f32_16x16x32_bf16 v[74:77], v[160:163], v[212:215], v[74:77]
	v_mfma_f32_16x16x32_bf16 v[66:69], v[168:171], v[212:215], v[66:69]
	s_barrier
	v_mul_lo_u32 v148, s6, v185
	v_lshl_add_u64 v[216:217], s[48:49], 0, v[148:149]
	s_add_i32 s50, s74, s3
	v_lshl_add_u64 v[216:217], v[216:217], 0, v[146:147]
	s_mov_b32 m0, s50
	ds_read_b128 v[172:175], v195 offset:16384
	ds_read_b128 v[176:179], v195 offset:17408
	ds_read_b128 v[180:183], v195 offset:18432
	ds_read_b128 v[196:199], v195 offset:19456
	ds_read_b128 v[200:203], v195 offset:20480
	ds_read_b128 v[204:207], v195 offset:21504
	ds_read_b128 v[208:211], v195 offset:22528
	ds_read_b128 v[212:215], v195 offset:23552
	global_load_lds_dwordx4 v[216:217], off
	v_mul_lo_u32 v218, s6, v187
	v_mov_b32_e32 v219, v149
	s_add_i32 m0, s50, 0x2000
	s_lshl_b64 s[50:51], s[6:7], 7
	v_lshl_add_u64 v[220:221], s[48:49], 0, v[218:219]
	s_add_u32 s48, s48, s50
	s_addc_u32 s49, s49, s51
	v_lshl_add_u64 v[220:221], v[220:221], 0, v[146:147]
	v_lshl_add_u64 v[222:223], s[48:49], 0, v[148:149]
	s_add_i32 s6, s75, s3
	global_load_lds_dwordx4 v[220:221], off
	v_lshl_add_u64 v[222:223], v[222:223], 0, v[146:147]
	s_mov_b32 m0, s6
	v_lshl_add_u64 v[218:219], s[48:49], 0, v[218:219]
	v_mul_lo_u32 v148, s62, v184
	global_load_lds_dwordx4 v[222:223], off
	v_lshl_add_u64 v[218:219], v[218:219], 0, v[146:147]
	s_add_i32 m0, s6, 0x2000
	v_lshl_add_u64 v[224:225], s[60:61], 0, v[148:149]
	v_mul_lo_u32 v226, s62, v186
	v_mov_b32_e32 v227, v149
	global_load_lds_dwordx4 v[218:219], off
	v_lshl_add_u64 v[224:225], v[224:225], 0, v[146:147]
	s_mov_b32 m0, s43
	v_lshl_add_u64 v[228:229], s[60:61], 0, v[226:227]
	global_load_lds_dwordx4 v[224:225], off
	v_lshl_add_u64 v[228:229], v[228:229], 0, v[146:147]
	s_mov_b32 m0, s65
	s_nop 0
	global_load_lds_dwordx4 v[228:229], off
	s_waitcnt vmcnt(8)
	s_waitcnt lgkmcnt(0)
	s_barrier
; #define PG8_STAGE(bufoff, gbase, RR, ld) do { _Pragma("unroll") for (int _i = 0; _i < 2; ++_i) \
;         __builtin_amdgcn_global_load_lds((const unsigned*)((const char*)(gbase) + (RR)[_i] * (ld) + C2[_i]), (LAS unsigned*)(lds + (bufoff) + ldsw + _i * 8192), 16, 0, 0); } while (0)
; #define PG8_LDA(dst, b, h) do { _Pragma("unroll") for (int m = 0; m < 4; ++m) _Pragma("unroll") for (int k = 0; k < 2; ++k) dst[m][k] = *(const LAS bf16x8*)(lds + PG8_SA(b, h) + aoff + m * 2048 + k * 1024); } while (0)
; #define PG8_LDB(dst, b, h) do { _Pragma("unroll") for (int n = 0; n < 2; ++n) _Pragma("unroll") for (int k = 0; k < 2; ++k) dst[n][k] = *(const LAS bf16x8*)(lds + PG8_SB(b, h) + boff + n * 2048 + k * 1024); } while (0)
; #define PG8_MMA(ai, bj, At, Bt) do { __builtin_amdgcn_s_setprio(1); _Pragma("unroll") for (int m = 0; m < 4; ++m) _Pragma("unroll") for (int n = 0; n < 2; ++n) _Pragma("unroll") for (int k = 0; k < 2; ++k) \
;         acc[ai][bj][m][n] = __builtin_amdgcn_mfma_f32_16x16x32_bf16(Bt[n][k], At[m][k], acc[ai][bj][m][n], 0, 0, 0); __builtin_amdgcn_s_setprio(0); } while (0)
; #define PG8_WAIT_V(n) asm volatile("s_waitcnt vmcnt(" #n ")" ::: "memory")
; #define PG8_WAIT_L(n) asm volatile("s_waitcnt lgkmcnt(" #n ")" ::: "memory")
; #define PG8_BAR __builtin_amdgcn_s_barrier()
; #define PG8_SCHED __builtin_amdgcn_sched_barrier(0)
; template <class Sched, class Epi>
; __device__ __forceinline__ void gemm_run(LAS unsigned char* lds, const Sched& S, const Epi& E) {
;     ...
;             PG8_WAIT_V(8); PG8_WAIT_L(0); PG8_BAR; PG8_MMA(1, 0, At, B0); PG8_MMA(1, 1, At, B1); PG8_BAR; PG8_SCHED;
;             PG8_LDB(B0, 1, 0); PG8_LDB(B1, 1, 1); PG8_SCHED; PG8_LDA(At, 1, 0); PG8_STAGE(PG8_SA(0, 1), a2 + (size_t)HALF * la2, RA, la2);
;             PG8_WAIT_V(8); PG8_WAIT_L(0); PG8_BAR; PG8_MMA(0, 0, At, B0); PG8_MMA(0, 1, At, B1); PG8_BAR; PG8_SCHED;
	s_waitcnt lgkmcnt(0)
	v_mfma_f32_16x16x32_bf16 v[62:65], v[134:137], v[172:175], 0
	v_mfma_f32_16x16x32_bf16 v[54:57], v[142:145], v[172:175], 0
	v_mfma_f32_16x16x32_bf16 v[46:49], v[134:137], v[180:183], 0
	v_mfma_f32_16x16x32_bf16 v[38:41], v[142:145], v[180:183], 0
	v_mfma_f32_16x16x32_bf16 v[30:33], v[134:137], v[200:203], 0
	v_mfma_f32_16x16x32_bf16 v[22:25], v[142:145], v[200:203], 0
	v_mfma_f32_16x16x32_bf16 v[14:17], v[134:137], v[208:211], 0
	v_mfma_f32_16x16x32_bf16 v[6:9], v[142:145], v[208:211], 0
	v_mfma_f32_16x16x32_bf16 v[62:65], v[138:141], v[176:179], v[62:65]
	v_mfma_f32_16x16x32_bf16 v[54:57], v[152:155], v[176:179], v[54:57]
	v_mfma_f32_16x16x32_bf16 v[46:49], v[138:141], v[196:199], v[46:49]
	v_mfma_f32_16x16x32_bf16 v[38:41], v[152:155], v[196:199], v[38:41]
	v_mfma_f32_16x16x32_bf16 v[30:33], v[138:141], v[204:207], v[30:33]
	v_mfma_f32_16x16x32_bf16 v[22:25], v[152:155], v[204:207], v[22:25]
	v_mfma_f32_16x16x32_bf16 v[14:17], v[138:141], v[212:215], v[14:17]
	v_mfma_f32_16x16x32_bf16 v[6:9], v[152:155], v[212:215], v[6:9]
	v_mfma_f32_16x16x32_bf16 v[58:61], v[156:159], v[172:175], 0
	v_mfma_f32_16x16x32_bf16 v[50:53], v[164:167], v[172:175], 0
	v_mfma_f32_16x16x32_bf16 v[42:45], v[156:159], v[180:183], 0
	v_mfma_f32_16x16x32_bf16 v[34:37], v[164:167], v[180:183], 0
	v_mfma_f32_16x16x32_bf16 v[26:29], v[156:159], v[200:203], 0
	v_mfma_f32_16x16x32_bf16 v[18:21], v[164:167], v[200:203], 0
	v_mfma_f32_16x16x32_bf16 v[10:13], v[156:159], v[208:211], 0
	v_mfma_f32_16x16x32_bf16 v[2:5], v[164:167], v[208:211], 0
	v_mfma_f32_16x16x32_bf16 v[58:61], v[160:163], v[176:179], v[58:61]
	v_mfma_f32_16x16x32_bf16 v[50:53], v[168:171], v[176:179], v[50:53]
	v_mfma_f32_16x16x32_bf16 v[42:45], v[160:163], v[196:199], v[42:45]
	v_mfma_f32_16x16x32_bf16 v[34:37], v[168:171], v[196:199], v[34:37]
	v_mfma_f32_16x16x32_bf16 v[26:29], v[160:163], v[204:207], v[26:29]
	v_mfma_f32_16x16x32_bf16 v[18:21], v[168:171], v[204:207], v[18:21]
	v_mfma_f32_16x16x32_bf16 v[10:13], v[160:163], v[212:215], v[10:13]
	v_mfma_f32_16x16x32_bf16 v[2:5], v[168:171], v[212:215], v[2:5]
	s_barrier
	s_add_i32 s6, 0, 0x18000
	s_add_i32 s50, 0, 0x1c000
	v_add_u32_e32 v152, s6, v189
	v_add_u32_e32 v168, s50, v189
	ds_read_b128 v[134:137], v152
	ds_read_b128 v[138:141], v152 offset:1024
	ds_read_b128 v[142:145], v152 offset:2048
	ds_read_b128 v[152:155], v152 offset:3072
	ds_read_b128 v[156:159], v168
	ds_read_b128 v[160:163], v168 offset:1024
	ds_read_b128 v[164:167], v168 offset:2048
	ds_read_b128 v[168:171], v168 offset:3072
	s_mov_b32 s63, s7
	s_lshl_b64 s[48:49], s[62:63], 7
	s_add_u32 s48, s60, s48
	s_addc_u32 s49, s61, s49
	v_lshl_add_u64 v[230:231], s[48:49], 0, v[148:149]
	s_mov_b32 m0, s66
	v_lshl_add_u64 v[230:231], v[230:231], 0, v[146:147]
	v_lshl_add_u64 v[226:227], s[48:49], 0, v[226:227]
	ds_read_b128 v[172:175], v195 offset:32768
	ds_read_b128 v[176:179], v195 offset:33792
	ds_read_b128 v[180:183], v195 offset:34816
	ds_read_b128 v[196:199], v195 offset:35840
	ds_read_b128 v[200:203], v195 offset:36864
	ds_read_b128 v[204:207], v195 offset:37888
	ds_read_b128 v[208:211], v195 offset:38912
	ds_read_b128 v[212:215], v195 offset:39936
	global_load_lds_dwordx4 v[230:231], off
	v_lshl_add_u64 v[226:227], v[226:227], 0, v[146:147]
	s_mov_b32 m0, s67
	s_nop 0
	global_load_lds_dwordx4 v[226:227], off
	s_waitcnt vmcnt(8)
	s_waitcnt lgkmcnt(0)
	s_barrier
	s_waitcnt lgkmcnt(0)
	v_mfma_f32_16x16x32_bf16 v[126:129], v[134:137], v[172:175], v[126:129]
	v_mfma_f32_16x16x32_bf16 v[118:121], v[142:145], v[172:175], v[118:121]
	v_mfma_f32_16x16x32_bf16 v[110:113], v[134:137], v[180:183], v[110:113]
	v_mfma_f32_16x16x32_bf16 v[102:105], v[142:145], v[180:183], v[102:105]
	v_mfma_f32_16x16x32_bf16 v[94:97], v[134:137], v[200:203], v[94:97]
	v_mfma_f32_16x16x32_bf16 v[86:89], v[142:145], v[200:203], v[86:89]
	v_mfma_f32_16x16x32_bf16 v[78:81], v[134:137], v[208:211], v[78:81]
	v_mfma_f32_16x16x32_bf16 v[70:73], v[142:145], v[208:211], v[70:73]
	v_mfma_f32_16x16x32_bf16 v[126:129], v[138:141], v[176:179], v[126:129]
	v_mfma_f32_16x16x32_bf16 v[118:121], v[152:155], v[176:179], v[118:121]
	v_mfma_f32_16x16x32_bf16 v[110:113], v[138:141], v[196:199], v[110:113]
	v_mfma_f32_16x16x32_bf16 v[102:105], v[152:155], v[196:199], v[102:105]
	v_mfma_f32_16x16x32_bf16 v[94:97], v[138:141], v[204:207], v[94:97]
	v_mfma_f32_16x16x32_bf16 v[86:89], v[152:155], v[204:207], v[86:89]
	v_mfma_f32_16x16x32_bf16 v[78:81], v[138:141], v[212:215], v[78:81]
	v_mfma_f32_16x16x32_bf16 v[70:73], v[152:155], v[212:215], v[70:73]
	v_mfma_f32_16x16x32_bf16 v[122:125], v[156:159], v[172:175], v[122:125]
	v_mfma_f32_16x16x32_bf16 v[114:117], v[164:167], v[172:175], v[114:117]
	v_mfma_f32_16x16x32_bf16 v[106:109], v[156:159], v[180:183], v[106:109]
	v_mfma_f32_16x16x32_bf16 v[98:101], v[164:167], v[180:183], v[98:101]
	v_mfma_f32_16x16x32_bf16 v[90:93], v[156:159], v[200:203], v[90:93]
	v_mfma_f32_16x16x32_bf16 v[82:85], v[164:167], v[200:203], v[82:85]
	v_mfma_f32_16x16x32_bf16 v[74:77], v[156:159], v[208:211], v[74:77]
	v_mfma_f32_16x16x32_bf16 v[66:69], v[164:167], v[208:211], v[66:69]
	v_mfma_f32_16x16x32_bf16 v[122:125], v[160:163], v[176:179], v[122:125]
	v_mfma_f32_16x16x32_bf16 v[114:117], v[168:171], v[176:179], v[114:117]
	v_mfma_f32_16x16x32_bf16 v[106:109], v[160:163], v[196:199], v[106:109]
	v_mfma_f32_16x16x32_bf16 v[98:101], v[168:171], v[196:199], v[98:101]
	v_mfma_f32_16x16x32_bf16 v[90:93], v[160:163], v[204:207], v[90:93]
	v_mfma_f32_16x16x32_bf16 v[82:85], v[168:171], v[204:207], v[82:85]
	v_mfma_f32_16x16x32_bf16 v[74:77], v[160:163], v[212:215], v[74:77]
	v_mfma_f32_16x16x32_bf16 v[66:69], v[168:171], v[212:215], v[66:69]
	s_barrier
; #define PG8_STAGE(bufoff, gbase, RR, ld) do { _Pragma("unroll") for (int _i = 0; _i < 2; ++_i) \
;         __builtin_amdgcn_global_load_lds((const unsigned*)((const char*)(gbase) + (RR)[_i] * (ld) + C2[_i]), (LAS unsigned*)(lds + (bufoff) + ldsw + _i * 8192), 16, 0, 0); } while (0)
; #define PG8_LDA(dst, b, h) do { _Pragma("unroll") for (int m = 0; m < 4; ++m) _Pragma("unroll") for (int k = 0; k < 2; ++k) dst[m][k] = *(const LAS bf16x8*)(lds + PG8_SA(b, h) + aoff + m * 2048 + k * 1024); } while (0)
; #define PG8_MMA(ai, bj, At, Bt) do { __builtin_amdgcn_s_setprio(1); _Pragma("unroll") for (int m = 0; m < 4; ++m) _Pragma("unroll") for (int n = 0; n < 2; ++n) _Pragma("unroll") for (int k = 0; k < 2; ++k) \
;         acc[ai][bj][m][n] = __builtin_amdgcn_mfma_f32_16x16x32_bf16(Bt[n][k], At[m][k], acc[ai][bj][m][n], 0, 0, 0); __builtin_amdgcn_s_setprio(0); } while (0)
; #define PG8_WAIT_V(n) asm volatile("s_waitcnt vmcnt(" #n ")" ::: "memory")
; #define PG8_WAIT_L(n) asm volatile("s_waitcnt lgkmcnt(" #n ")" ::: "memory")
; #define PG8_BAR __builtin_amdgcn_s_barrier()
; #define PG8_SCHED __builtin_amdgcn_sched_barrier(0)
; template <class Sched, class Epi>
; __device__ __forceinline__ void gemm_run(LAS unsigned char* lds, const Sched& S, const Epi& E) {
;     ...
;             PG8_LDA(At, 1, 1); PG8_STAGE(PG8_SB(1, 0), b3, RB, lb2); PG8_STAGE(PG8_SB(1, 1), b3 + (size_t)HALF * lb2, RB, lb2); PG8_STAGE(PG8_SA(1, 0), a3, RA, la2);
;             PG8_WAIT_V(8); PG8_WAIT_L(0); PG8_BAR; PG8_MMA(1, 0, At, B0); PG8_MMA(1, 1, At, B1); PG8_BAR; PG8_SCHED;
;         }
	s_add_i32 s6, s6, s3
	v_lshl_add_u64 v[216:217], v[216:217], 0, s[8:9]
	s_mov_b32 m0, s6
	ds_read_b128 v[172:175], v195 offset:49152
	ds_read_b128 v[176:179], v195 offset:50176
	ds_read_b128 v[180:183], v195 offset:51200
	ds_read_b128 v[196:199], v195 offset:52224
	ds_read_b128 v[200:203], v195 offset:53248
	ds_read_b128 v[204:207], v195 offset:54272
	ds_read_b128 v[208:211], v195 offset:55296
	ds_read_b128 v[212:215], v195 offset:56320
	global_load_lds_dwordx4 v[216:217], off
	v_lshl_add_u64 v[216:217], v[220:221], 0, s[8:9]
	s_add_i32 m0, s6, 0x2000
	s_add_i32 s6, s50, s3
	global_load_lds_dwordx4 v[216:217], off
	v_lshl_add_u64 v[216:217], v[222:223], 0, s[8:9]
	s_mov_b32 m0, s6
	s_nop 0
	global_load_lds_dwordx4 v[216:217], off
	v_lshl_add_u64 v[216:217], v[218:219], 0, s[8:9]
	s_add_i32 m0, s6, 0x2000
	s_nop 0
	global_load_lds_dwordx4 v[216:217], off
	v_lshl_add_u64 v[216:217], v[224:225], 0, s[8:9]
	s_mov_b32 m0, s68
	s_nop 0
	global_load_lds_dwordx4 v[216:217], off
	v_lshl_add_u64 v[216:217], v[228:229], 0, s[8:9]
	s_mov_b32 m0, s69
	s_nop 0
	global_load_lds_dwordx4 v[216:217], off
	s_waitcnt vmcnt(8)
	s_waitcnt lgkmcnt(0)
	s_barrier
	s_waitcnt lgkmcnt(0)
	v_mfma_f32_16x16x32_bf16 v[62:65], v[134:137], v[172:175], v[62:65]
	v_mfma_f32_16x16x32_bf16 v[54:57], v[142:145], v[172:175], v[54:57]
	v_mfma_f32_16x16x32_bf16 v[46:49], v[134:137], v[180:183], v[46:49]
	v_mfma_f32_16x16x32_bf16 v[38:41], v[142:145], v[180:183], v[38:41]
	v_mfma_f32_16x16x32_bf16 v[30:33], v[134:137], v[200:203], v[30:33]
	v_mfma_f32_16x16x32_bf16 v[22:25], v[142:145], v[200:203], v[22:25]
	v_mfma_f32_16x16x32_bf16 v[14:17], v[134:137], v[208:211], v[14:17]
	v_mfma_f32_16x16x32_bf16 v[6:9], v[142:145], v[208:211], v[6:9]
	v_mfma_f32_16x16x32_bf16 v[62:65], v[138:141], v[176:179], v[62:65]
	v_mfma_f32_16x16x32_bf16 v[54:57], v[152:155], v[176:179], v[54:57]
	v_mfma_f32_16x16x32_bf16 v[46:49], v[138:141], v[196:199], v[46:49]
	v_mfma_f32_16x16x32_bf16 v[38:41], v[152:155], v[196:199], v[38:41]
	v_mfma_f32_16x16x32_bf16 v[30:33], v[138:141], v[204:207], v[30:33]
	v_mfma_f32_16x16x32_bf16 v[22:25], v[152:155], v[204:207], v[22:25]
	v_mfma_f32_16x16x32_bf16 v[14:17], v[138:141], v[212:215], v[14:17]
	v_mfma_f32_16x16x32_bf16 v[6:9], v[152:155], v[212:215], v[6:9]
	v_mfma_f32_16x16x32_bf16 v[58:61], v[156:159], v[172:175], v[58:61]
	v_mfma_f32_16x16x32_bf16 v[50:53], v[164:167], v[172:175], v[50:53]
	v_mfma_f32_16x16x32_bf16 v[42:45], v[156:159], v[180:183], v[42:45]
	v_mfma_f32_16x16x32_bf16 v[34:37], v[164:167], v[180:183], v[34:37]
	v_mfma_f32_16x16x32_bf16 v[26:29], v[156:159], v[200:203], v[26:29]
	v_mfma_f32_16x16x32_bf16 v[18:21], v[164:167], v[200:203], v[18:21]
	v_mfma_f32_16x16x32_bf16 v[10:13], v[156:159], v[208:211], v[10:13]
	v_mfma_f32_16x16x32_bf16 v[2:5], v[164:167], v[208:211], v[2:5]
	v_mfma_f32_16x16x32_bf16 v[58:61], v[160:163], v[176:179], v[58:61]
	v_mfma_f32_16x16x32_bf16 v[50:53], v[168:171], v[176:179], v[50:53]
	v_mfma_f32_16x16x32_bf16 v[42:45], v[160:163], v[196:199], v[42:45]
	v_mfma_f32_16x16x32_bf16 v[34:37], v[168:171], v[196:199], v[34:37]
	v_mfma_f32_16x16x32_bf16 v[26:29], v[160:163], v[204:207], v[26:29]
	v_mfma_f32_16x16x32_bf16 v[18:21], v[168:171], v[204:207], v[18:21]
	v_mfma_f32_16x16x32_bf16 v[10:13], v[160:163], v[212:215], v[10:13]
	v_mfma_f32_16x16x32_bf16 v[2:5], v[168:171], v[212:215], v[2:5]
	s_barrier
	s_add_u32 s58, s58, 0x100
	s_addc_u32 s59, s59, 0
	s_cmp_ge_i32 s47, s81
	s_mov_b32 s6, s47
	s_cbranch_scc0 .LBB0_806
	.p2align 6

; #define PG8_STAGE(bufoff, gbase, RR, ld) do { _Pragma("unroll") for (int _i = 0; _i < 2; ++_i) \
;         __builtin_amdgcn_global_load_lds((const unsigned*)((const char*)(gbase) + (RR)[_i] * (ld) + C2[_i]), (LAS unsigned*)(lds + (bufoff) + ldsw + _i * 8192), 16, 0, 0); } while (0)
; #define PG8_LDA(dst, b, h) do { _Pragma("unroll") for (int m = 0; m < 4; ++m) _Pragma("unroll") for (int k = 0; k < 2; ++k) dst[m][k] = *(const LAS bf16x8*)(lds + PG8_SA(b, h) + aoff + m * 2048 + k * 1024); } while (0)
; #define PG8_LDB(dst, b, h) do { _Pragma("unroll") for (int n = 0; n < 2; ++n) _Pragma("unroll") for (int k = 0; k < 2; ++k) dst[n][k] = *(const LAS bf16x8*)(lds + PG8_SB(b, h) + boff + n * 2048 + k * 1024); } while (0)
; #define PG8_WAIT_V(n) asm volatile("s_waitcnt vmcnt(" #n ")" ::: "memory")
; template <class Sched, class Epi>
; __device__ __forceinline__ void gemm_run(LAS unsigned char* lds, const Sched& S, const Epi& E) {
;     ...
;     f32x4 acc[2][2][4][2];
; #pragma unroll
;     for (int a = 0; a < 2; ++a)
; #pragma unroll
;         for (int b = 0; b < 2; ++b)
; #pragma unroll
;             for (int m = 0; m < 4; ++m)
; #pragma unroll
;                 for (int n = 0; n < 2; ++n) acc[a][b][m][n] = (f32x4){0.f, 0.f, 0.f, 0.f};
;     ...
;     for (;;) {
;         const bool has_next = S.next(ui + 1, nxt);
;         const char* nA = has_next ? nxt.A : cA; const char* nB = has_next ? nxt.B : cB; const unsigned nlda = has_next ? nxt.lda : lda, nldb = has_next ? nxt.ldb : ldb;
;         const int nt = cur.nt;
;         for (int t = 0; t < nt; t += 2) {
;             const bool last = (t == nt - 2);
;             const char* a1 = cA + (size_t)(t + 1) * kstep;
;             const char* a2 = last ? nA : cA + (size_t)(t + 2) * kstep; const char* b2 = last ? nB : cB + (size_t)(t + 2) * kstep;
;             const unsigned la2 = last ? nlda : lda, lb2 = last ? nldb : ldb;
;             const char* a3 = a2 + kstep; const char* b3 = b2 + kstep;
;             PG8_LDB(B0, 0, 0); PG8_LDB(B1, 0, 1); PG8_SCHED; PG8_LDA(At, 0, 0); PG8_STAGE(PG8_SA(1, 1), a1 + (size_t)HALF * lda, RA, lda);
;             PG8_WAIT_V(8); PG8_WAIT_L(0); PG8_BAR; PG8_MMA(0, 0, At, B0); PG8_MMA(0, 1, At, B1); PG8_BAR; PG8_SCHED;
;             PG8_LDA(At, 0, 1); PG8_STAGE(PG8_SB(0, 0), b2, RB, lb2); PG8_STAGE(PG8_SB(0, 1), b2 + (size_t)HALF * lb2, RB, lb2); PG8_STAGE(PG8_SA(0, 0), a2, RA, la2);
.LBB0_893:
	s_add_u32 s19, s38, 0x100
	s_addc_u32 s31, s39, 0
	v_lshl_add_u64 v[130:131], s[36:37], 0, v[168:169]
	v_lshl_add_u64 v[132:133], s[36:37], 0, v[170:171]
	s_mov_b32 s44, -2
	s_mov_b64 s[38:39], 0
	s_waitcnt lgkmcnt(0)
	ds_read_b128 v[134:137], v191
	ds_read_b128 v[138:141], v191 offset:1024
	ds_read_b128 v[142:145], v191 offset:2048
	ds_read_b128 v[146:149], v191 offset:3072
	ds_read_b128 v[150:153], v192
	ds_read_b128 v[172:175], v192 offset:1024
	ds_read_b128 v[176:179], v192 offset:2048
	ds_read_b128 v[180:183], v192 offset:3072
	s_add_u32 s40, s36, s38
	s_addc_u32 s41, s37, s39
	s_add_u32 s40, s40, 0x100
	s_addc_u32 s41, s41, 0
	s_add_u32 s45, s19, s38
	s_addc_u32 s46, s31, s39
	s_cmpk_eq_i32 s38, 0xf00
	s_cselect_b32 s43, s21, s41
	s_cselect_b32 s42, s20, s40
	s_cselect_b32 s41, s29, s46
	s_cselect_b32 s40, s28, s45
	v_lshl_add_u64 v[224:225], v[130:131], 0, s[38:39]
	s_add_i32 m0, s33, 0xc000
	ds_read_b128 v[184:187], v193
	ds_read_b128 v[196:199], v193 offset:1024
	ds_read_b128 v[200:203], v193 offset:2048
	ds_read_b128 v[204:207], v193 offset:3072
	ds_read_b128 v[208:211], v193 offset:4096
	ds_read_b128 v[212:215], v193 offset:5120
	ds_read_b128 v[216:219], v193 offset:6144
	ds_read_b128 v[220:223], v193 offset:7168
	global_load_lds_dwordx4 v[224:225], off
	v_lshl_add_u64 v[224:225], v[132:133], 0, s[38:39]
	s_add_i32 m0, s33, 0xe000
	s_nop 0
	global_load_lds_dwordx4 v[224:225], off
	s_waitcnt vmcnt(8)
	s_waitcnt lgkmcnt(0)
	s_barrier
	s_waitcnt lgkmcnt(0)
	v_mfma_f32_16x16x32_bf16 v[126:129], v[134:137], v[184:187], 0
	v_mfma_f32_16x16x32_bf16 v[122:125], v[142:145], v[184:187], 0
	v_mfma_f32_16x16x32_bf16 v[110:113], v[134:137], v[200:203], 0
	v_mfma_f32_16x16x32_bf16 v[106:109], v[142:145], v[200:203], 0
	v_mfma_f32_16x16x32_bf16 v[94:97], v[134:137], v[208:211], 0
	v_mfma_f32_16x16x32_bf16 v[90:93], v[142:145], v[208:211], 0
	v_mfma_f32_16x16x32_bf16 v[78:81], v[134:137], v[216:219], 0
	v_mfma_f32_16x16x32_bf16 v[74:77], v[142:145], v[216:219], 0
	v_mfma_f32_16x16x32_bf16 v[126:129], v[138:141], v[196:199], v[126:129]
	v_mfma_f32_16x16x32_bf16 v[122:125], v[146:149], v[196:199], v[122:125]
	v_mfma_f32_16x16x32_bf16 v[110:113], v[138:141], v[204:207], v[110:113]
	v_mfma_f32_16x16x32_bf16 v[106:109], v[146:149], v[204:207], v[106:109]
	v_mfma_f32_16x16x32_bf16 v[94:97], v[138:141], v[212:215], v[94:97]
	v_mfma_f32_16x16x32_bf16 v[90:93], v[146:149], v[212:215], v[90:93]
	v_mfma_f32_16x16x32_bf16 v[78:81], v[138:141], v[220:223], v[78:81]
	v_mfma_f32_16x16x32_bf16 v[74:77], v[146:149], v[220:223], v[74:77]
	v_mfma_f32_16x16x32_bf16 v[118:121], v[150:153], v[184:187], 0
	v_mfma_f32_16x16x32_bf16 v[114:117], v[176:179], v[184:187], 0
	v_mfma_f32_16x16x32_bf16 v[102:105], v[150:153], v[200:203], 0
	v_mfma_f32_16x16x32_bf16 v[98:101], v[176:179], v[200:203], 0
	v_mfma_f32_16x16x32_bf16 v[86:89], v[150:153], v[208:211], 0
	v_mfma_f32_16x16x32_bf16 v[82:85], v[176:179], v[208:211], 0
	v_mfma_f32_16x16x32_bf16 v[70:73], v[150:153], v[216:219], 0
	v_mfma_f32_16x16x32_bf16 v[66:69], v[176:179], v[216:219], 0
	v_mfma_f32_16x16x32_bf16 v[118:121], v[172:175], v[196:199], v[118:121]
	v_mfma_f32_16x16x32_bf16 v[114:117], v[180:183], v[196:199], v[114:117]
	v_mfma_f32_16x16x32_bf16 v[102:105], v[172:175], v[204:207], v[102:105]
	v_mfma_f32_16x16x32_bf16 v[98:101], v[180:183], v[204:207], v[98:101]
	v_mfma_f32_16x16x32_bf16 v[86:89], v[172:175], v[212:215], v[86:89]
	v_mfma_f32_16x16x32_bf16 v[82:85], v[180:183], v[212:215], v[82:85]
	v_mfma_f32_16x16x32_bf16 v[70:73], v[172:175], v[220:223], v[70:73]
	v_mfma_f32_16x16x32_bf16 v[66:69], v[180:183], v[220:223], v[66:69]
	s_barrier
	v_lshl_add_u64 v[224:225], s[40:41], 0, v[156:157]
	s_add_i32 s45, s61, s3
	v_lshl_add_u64 v[224:225], v[224:225], 0, v[154:155]
	s_mov_b32 m0, s45
	ds_read_b128 v[184:187], v193 offset:16384
	ds_read_b128 v[196:199], v193 offset:17408
	ds_read_b128 v[200:203], v193 offset:18432
	ds_read_b128 v[204:207], v193 offset:19456
	ds_read_b128 v[208:211], v193 offset:20480
	ds_read_b128 v[212:215], v193 offset:21504
	ds_read_b128 v[216:219], v193 offset:22528
	ds_read_b128 v[220:223], v193 offset:23552
	global_load_lds_dwordx4 v[224:225], off
	s_add_i32 m0, s45, 0x2000
	s_add_u32 s46, s40, 0x80000
	v_lshl_add_u64 v[226:227], s[40:41], 0, v[160:161]
	s_addc_u32 s47, s41, 0
	v_lshl_add_u64 v[226:227], v[226:227], 0, v[154:155]
	v_lshl_add_u64 v[228:229], s[46:47], 0, v[156:157]
	s_add_i32 s45, s62, s3
	global_load_lds_dwordx4 v[226:227], off
	v_lshl_add_u64 v[228:229], v[228:229], 0, v[154:155]
	s_mov_b32 m0, s45
	v_lshl_add_u64 v[230:231], s[42:43], 0, v[164:165]
	global_load_lds_dwordx4 v[228:229], off
	v_lshl_add_u64 v[228:229], s[46:47], 0, v[160:161]
	v_lshl_add_u64 v[228:229], v[228:229], 0, v[154:155]
	s_add_i32 m0, s45, 0x2000
	v_lshl_add_u64 v[230:231], v[230:231], 0, v[154:155]
	global_load_lds_dwordx4 v[228:229], off
	v_lshl_add_u64 v[228:229], s[42:43], 0, v[162:163]
	v_lshl_add_u64 v[228:229], v[228:229], 0, v[154:155]
	s_mov_b32 m0, s33
	s_nop 0
	global_load_lds_dwordx4 v[228:229], off
	s_mov_b32 m0, s35
	s_nop 0
	global_load_lds_dwordx4 v[230:231], off
	s_waitcnt vmcnt(8)
	s_waitcnt lgkmcnt(0)
	s_barrier
; #define PG8_STAGE(bufoff, gbase, RR, ld) do { _Pragma("unroll") for (int _i = 0; _i < 2; ++_i) \
;         __builtin_amdgcn_global_load_lds((const unsigned*)((const char*)(gbase) + (RR)[_i] * (ld) + C2[_i]), (LAS unsigned*)(lds + (bufoff) + ldsw + _i * 8192), 16, 0, 0); } while (0)
; #define PG8_LDA(dst, b, h) do { _Pragma("unroll") for (int m = 0; m < 4; ++m) _Pragma("unroll") for (int k = 0; k < 2; ++k) dst[m][k] = *(const LAS bf16x8*)(lds + PG8_SA(b, h) + aoff + m * 2048 + k * 1024); } while (0)
; #define PG8_LDB(dst, b, h) do { _Pragma("unroll") for (int n = 0; n < 2; ++n) _Pragma("unroll") for (int k = 0; k < 2; ++k) dst[n][k] = *(const LAS bf16x8*)(lds + PG8_SB(b, h) + boff + n * 2048 + k * 1024); } while (0)
; #define PG8_MMA(ai, bj, At, Bt) do { __builtin_amdgcn_s_setprio(1); _Pragma("unroll") for (int m = 0; m < 4; ++m) _Pragma("unroll") for (int n = 0; n < 2; ++n) _Pragma("unroll") for (int k = 0; k < 2; ++k) \
;         acc[ai][bj][m][n] = __builtin_amdgcn_mfma_f32_16x16x32_bf16(Bt[n][k], At[m][k], acc[ai][bj][m][n], 0, 0, 0); __builtin_amdgcn_s_setprio(0); } while (0)
; #define PG8_WAIT_V(n) asm volatile("s_waitcnt vmcnt(" #n ")" ::: "memory")
; #define PG8_WAIT_L(n) asm volatile("s_waitcnt lgkmcnt(" #n ")" ::: "memory")
; #define PG8_BAR __builtin_amdgcn_s_barrier()
; #define PG8_SCHED __builtin_amdgcn_sched_barrier(0)
; template <class Sched, class Epi>
; __device__ __forceinline__ void gemm_run(LAS unsigned char* lds, const Sched& S, const Epi& E) {
;     ...
;             PG8_WAIT_V(8); PG8_WAIT_L(0); PG8_BAR; PG8_MMA(1, 0, At, B0); PG8_MMA(1, 1, At, B1); PG8_BAR; PG8_SCHED;
;             PG8_LDB(B0, 1, 0); PG8_LDB(B1, 1, 1); PG8_SCHED; PG8_LDA(At, 1, 0); PG8_STAGE(PG8_SA(0, 1), a2 + (size_t)HALF * la2, RA, la2);
;             PG8_WAIT_V(8); PG8_WAIT_L(0); PG8_BAR; PG8_MMA(0, 0, At, B0); PG8_MMA(0, 1, At, B1); PG8_BAR; PG8_SCHED;
	s_waitcnt lgkmcnt(0)
	v_mfma_f32_16x16x32_bf16 v[62:65], v[134:137], v[184:187], 0
	v_mfma_f32_16x16x32_bf16 v[58:61], v[142:145], v[184:187], 0
	v_mfma_f32_16x16x32_bf16 v[46:49], v[134:137], v[200:203], 0
	v_mfma_f32_16x16x32_bf16 v[42:45], v[142:145], v[200:203], 0
	v_mfma_f32_16x16x32_bf16 v[30:33], v[134:137], v[208:211], 0
	v_mfma_f32_16x16x32_bf16 v[26:29], v[142:145], v[208:211], 0
	v_mfma_f32_16x16x32_bf16 v[14:17], v[134:137], v[216:219], 0
	v_mfma_f32_16x16x32_bf16 v[10:13], v[142:145], v[216:219], 0
	v_mfma_f32_16x16x32_bf16 v[62:65], v[138:141], v[196:199], v[62:65]
	v_mfma_f32_16x16x32_bf16 v[58:61], v[146:149], v[196:199], v[58:61]
	v_mfma_f32_16x16x32_bf16 v[46:49], v[138:141], v[204:207], v[46:49]
	v_mfma_f32_16x16x32_bf16 v[42:45], v[146:149], v[204:207], v[42:45]
	v_mfma_f32_16x16x32_bf16 v[30:33], v[138:141], v[212:215], v[30:33]
	v_mfma_f32_16x16x32_bf16 v[26:29], v[146:149], v[212:215], v[26:29]
	v_mfma_f32_16x16x32_bf16 v[14:17], v[138:141], v[220:223], v[14:17]
	v_mfma_f32_16x16x32_bf16 v[10:13], v[146:149], v[220:223], v[10:13]
	v_mfma_f32_16x16x32_bf16 v[54:57], v[150:153], v[184:187], 0
	v_mfma_f32_16x16x32_bf16 v[50:53], v[176:179], v[184:187], 0
	v_mfma_f32_16x16x32_bf16 v[38:41], v[150:153], v[200:203], 0
	v_mfma_f32_16x16x32_bf16 v[34:37], v[176:179], v[200:203], 0
	v_mfma_f32_16x16x32_bf16 v[22:25], v[150:153], v[208:211], 0
	v_mfma_f32_16x16x32_bf16 v[18:21], v[176:179], v[208:211], 0
	v_mfma_f32_16x16x32_bf16 v[6:9], v[150:153], v[216:219], 0
	v_mfma_f32_16x16x32_bf16 v[2:5], v[176:179], v[216:219], 0
	v_mfma_f32_16x16x32_bf16 v[54:57], v[172:175], v[196:199], v[54:57]
	v_mfma_f32_16x16x32_bf16 v[50:53], v[180:183], v[196:199], v[50:53]
	v_mfma_f32_16x16x32_bf16 v[38:41], v[172:175], v[204:207], v[38:41]
	v_mfma_f32_16x16x32_bf16 v[34:37], v[180:183], v[204:207], v[34:37]
	v_mfma_f32_16x16x32_bf16 v[22:25], v[172:175], v[212:215], v[22:25]
	v_mfma_f32_16x16x32_bf16 v[18:21], v[180:183], v[212:215], v[18:21]
	v_mfma_f32_16x16x32_bf16 v[6:9], v[172:175], v[220:223], v[6:9]
	v_mfma_f32_16x16x32_bf16 v[2:5], v[180:183], v[220:223], v[2:5]
	s_barrier
	s_add_i32 s45, 0, 0x18000
	s_add_i32 s46, 0, 0x1c000
	v_add_u32_e32 v146, s45, v190
	v_add_u32_e32 v180, s46, v190
	ds_read_b128 v[134:137], v146
	ds_read_b128 v[138:141], v146 offset:1024
	ds_read_b128 v[142:145], v146 offset:2048
	ds_read_b128 v[146:149], v146 offset:3072
	ds_read_b128 v[150:153], v180
	ds_read_b128 v[172:175], v180 offset:1024
	ds_read_b128 v[176:179], v180 offset:2048
	ds_read_b128 v[180:183], v180 offset:3072
	s_add_u32 s42, s42, 0x80000
	s_addc_u32 s43, s43, 0
	v_lshl_add_u64 v[232:233], s[42:43], 0, v[162:163]
	s_mov_b32 m0, s52
	v_lshl_add_u64 v[232:233], v[232:233], 0, v[154:155]
	ds_read_b128 v[184:187], v193 offset:32768
	ds_read_b128 v[196:199], v193 offset:33792
	ds_read_b128 v[200:203], v193 offset:34816
	ds_read_b128 v[204:207], v193 offset:35840
	ds_read_b128 v[208:211], v193 offset:36864
	ds_read_b128 v[212:215], v193 offset:37888
	ds_read_b128 v[216:219], v193 offset:38912
	ds_read_b128 v[220:223], v193 offset:39936
	global_load_lds_dwordx4 v[232:233], off
	v_lshl_add_u64 v[232:233], s[42:43], 0, v[164:165]
	v_lshl_add_u64 v[232:233], v[232:233], 0, v[154:155]
	s_mov_b32 m0, s53
	s_nop 0
	global_load_lds_dwordx4 v[232:233], off
	s_waitcnt vmcnt(8)
	s_waitcnt lgkmcnt(0)
	s_barrier
	s_waitcnt lgkmcnt(0)
	v_mfma_f32_16x16x32_bf16 v[126:129], v[134:137], v[184:187], v[126:129]
	v_mfma_f32_16x16x32_bf16 v[122:125], v[142:145], v[184:187], v[122:125]
	v_mfma_f32_16x16x32_bf16 v[110:113], v[134:137], v[200:203], v[110:113]
	v_mfma_f32_16x16x32_bf16 v[106:109], v[142:145], v[200:203], v[106:109]
	v_mfma_f32_16x16x32_bf16 v[94:97], v[134:137], v[208:211], v[94:97]
	v_mfma_f32_16x16x32_bf16 v[90:93], v[142:145], v[208:211], v[90:93]
	v_mfma_f32_16x16x32_bf16 v[78:81], v[134:137], v[216:219], v[78:81]
	v_mfma_f32_16x16x32_bf16 v[74:77], v[142:145], v[216:219], v[74:77]
	v_mfma_f32_16x16x32_bf16 v[126:129], v[138:141], v[196:199], v[126:129]
	v_mfma_f32_16x16x32_bf16 v[122:125], v[146:149], v[196:199], v[122:125]
	v_mfma_f32_16x16x32_bf16 v[110:113], v[138:141], v[204:207], v[110:113]
	v_mfma_f32_16x16x32_bf16 v[106:109], v[146:149], v[204:207], v[106:109]
	v_mfma_f32_16x16x32_bf16 v[94:97], v[138:141], v[212:215], v[94:97]
	v_mfma_f32_16x16x32_bf16 v[90:93], v[146:149], v[212:215], v[90:93]
	v_mfma_f32_16x16x32_bf16 v[78:81], v[138:141], v[220:223], v[78:81]
	v_mfma_f32_16x16x32_bf16 v[74:77], v[146:149], v[220:223], v[74:77]
	v_mfma_f32_16x16x32_bf16 v[118:121], v[150:153], v[184:187], v[118:121]
	v_mfma_f32_16x16x32_bf16 v[114:117], v[176:179], v[184:187], v[114:117]
	v_mfma_f32_16x16x32_bf16 v[102:105], v[150:153], v[200:203], v[102:105]
	v_mfma_f32_16x16x32_bf16 v[98:101], v[176:179], v[200:203], v[98:101]
	v_mfma_f32_16x16x32_bf16 v[86:89], v[150:153], v[208:211], v[86:89]
	v_mfma_f32_16x16x32_bf16 v[82:85], v[176:179], v[208:211], v[82:85]
	v_mfma_f32_16x16x32_bf16 v[70:73], v[150:153], v[216:219], v[70:73]
	v_mfma_f32_16x16x32_bf16 v[66:69], v[176:179], v[216:219], v[66:69]
	v_mfma_f32_16x16x32_bf16 v[118:121], v[172:175], v[196:199], v[118:121]
	v_mfma_f32_16x16x32_bf16 v[114:117], v[180:183], v[196:199], v[114:117]
	v_mfma_f32_16x16x32_bf16 v[102:105], v[172:175], v[204:207], v[102:105]
	v_mfma_f32_16x16x32_bf16 v[98:101], v[180:183], v[204:207], v[98:101]
	v_mfma_f32_16x16x32_bf16 v[86:89], v[172:175], v[212:215], v[86:89]
	v_mfma_f32_16x16x32_bf16 v[82:85], v[180:183], v[212:215], v[82:85]
	v_mfma_f32_16x16x32_bf16 v[70:73], v[172:175], v[220:223], v[70:73]
	v_mfma_f32_16x16x32_bf16 v[66:69], v[180:183], v[220:223], v[66:69]
	s_barrier
; #define PG8_STAGE(bufoff, gbase, RR, ld) do { _Pragma("unroll") for (int _i = 0; _i < 2; ++_i) \
;         __builtin_amdgcn_global_load_lds((const unsigned*)((const char*)(gbase) + (RR)[_i] * (ld) + C2[_i]), (LAS unsigned*)(lds + (bufoff) + ldsw + _i * 8192), 16, 0, 0); } while (0)
; #define PG8_LDA(dst, b, h) do { _Pragma("unroll") for (int m = 0; m < 4; ++m) _Pragma("unroll") for (int k = 0; k < 2; ++k) dst[m][k] = *(const LAS bf16x8*)(lds + PG8_SA(b, h) + aoff + m * 2048 + k * 1024); } while (0)
; #define PG8_MMA(ai, bj, At, Bt) do { __builtin_amdgcn_s_setprio(1); _Pragma("unroll") for (int m = 0; m < 4; ++m) _Pragma("unroll") for (int n = 0; n < 2; ++n) _Pragma("unroll") for (int k = 0; k < 2; ++k) \
;         acc[ai][bj][m][n] = __builtin_amdgcn_mfma_f32_16x16x32_bf16(Bt[n][k], At[m][k], acc[ai][bj][m][n], 0, 0, 0); __builtin_amdgcn_s_setprio(0); } while (0)
; #define PG8_WAIT_V(n) asm volatile("s_waitcnt vmcnt(" #n ")" ::: "memory")
; #define PG8_WAIT_L(n) asm volatile("s_waitcnt lgkmcnt(" #n ")" ::: "memory")
; #define PG8_BAR __builtin_amdgcn_s_barrier()
; #define PG8_SCHED __builtin_amdgcn_sched_barrier(0)
; template <class Sched, class Epi>
; __device__ __forceinline__ void gemm_run(LAS unsigned char* lds, const Sched& S, const Epi& E) {
;     ...
;             PG8_LDA(At, 1, 1); PG8_STAGE(PG8_SB(1, 0), b3, RB, lb2); PG8_STAGE(PG8_SB(1, 1), b3 + (size_t)HALF * lb2, RB, lb2); PG8_STAGE(PG8_SA(1, 0), a3, RA, la2);
;             PG8_WAIT_V(8); PG8_WAIT_L(0); PG8_BAR; PG8_MMA(1, 0, At, B0); PG8_MMA(1, 1, At, B1); PG8_BAR; PG8_SCHED;
;         }
	s_add_i32 s42, s45, s3
	v_lshl_add_u64 v[224:225], v[224:225], 0, s[10:11]
	s_mov_b32 m0, s42
	ds_read_b128 v[184:187], v193 offset:49152
	ds_read_b128 v[196:199], v193 offset:50176
	ds_read_b128 v[200:203], v193 offset:51200
	ds_read_b128 v[204:207], v193 offset:52224
	ds_read_b128 v[208:211], v193 offset:53248
	ds_read_b128 v[212:215], v193 offset:54272
	ds_read_b128 v[216:219], v193 offset:55296
	ds_read_b128 v[220:223], v193 offset:56320
	global_load_lds_dwordx4 v[224:225], off
	s_add_i32 m0, s42, 0x2000
	s_add_u32 s40, s40, 0x80080
	v_lshl_add_u64 v[224:225], v[226:227], 0, s[10:11]
	s_addc_u32 s41, s41, 0
	global_load_lds_dwordx4 v[224:225], off
	v_lshl_add_u64 v[224:225], s[40:41], 0, v[156:157]
	s_add_i32 s42, s46, s3
	v_lshl_add_u64 v[224:225], v[224:225], 0, v[154:155]
	s_mov_b32 m0, s42
	s_nop 0
	global_load_lds_dwordx4 v[224:225], off
	v_lshl_add_u64 v[224:225], s[40:41], 0, v[160:161]
	v_lshl_add_u64 v[224:225], v[224:225], 0, v[154:155]
	s_add_i32 m0, s42, 0x2000
	s_nop 0
	global_load_lds_dwordx4 v[224:225], off
	v_lshl_add_u64 v[224:225], v[228:229], 0, s[10:11]
	s_mov_b32 m0, s55
	s_nop 0
	global_load_lds_dwordx4 v[224:225], off
	v_lshl_add_u64 v[224:225], v[230:231], 0, s[10:11]
	s_mov_b32 m0, s56
	s_nop 0
	global_load_lds_dwordx4 v[224:225], off
	s_waitcnt vmcnt(8)
	s_waitcnt lgkmcnt(0)
	s_barrier
	s_waitcnt lgkmcnt(0)
	v_mfma_f32_16x16x32_bf16 v[62:65], v[134:137], v[184:187], v[62:65]
	v_mfma_f32_16x16x32_bf16 v[58:61], v[142:145], v[184:187], v[58:61]
	v_mfma_f32_16x16x32_bf16 v[46:49], v[134:137], v[200:203], v[46:49]
	v_mfma_f32_16x16x32_bf16 v[42:45], v[142:145], v[200:203], v[42:45]
	v_mfma_f32_16x16x32_bf16 v[30:33], v[134:137], v[208:211], v[30:33]
	v_mfma_f32_16x16x32_bf16 v[26:29], v[142:145], v[208:211], v[26:29]
	v_mfma_f32_16x16x32_bf16 v[14:17], v[134:137], v[216:219], v[14:17]
	v_mfma_f32_16x16x32_bf16 v[10:13], v[142:145], v[216:219], v[10:13]
	v_mfma_f32_16x16x32_bf16 v[62:65], v[138:141], v[196:199], v[62:65]
	v_mfma_f32_16x16x32_bf16 v[58:61], v[146:149], v[196:199], v[58:61]
	v_mfma_f32_16x16x32_bf16 v[46:49], v[138:141], v[204:207], v[46:49]
	v_mfma_f32_16x16x32_bf16 v[42:45], v[146:149], v[204:207], v[42:45]
	v_mfma_f32_16x16x32_bf16 v[30:33], v[138:141], v[212:215], v[30:33]
	v_mfma_f32_16x16x32_bf16 v[26:29], v[146:149], v[212:215], v[26:29]
	v_mfma_f32_16x16x32_bf16 v[14:17], v[138:141], v[220:223], v[14:17]
	v_mfma_f32_16x16x32_bf16 v[10:13], v[146:149], v[220:223], v[10:13]
	v_mfma_f32_16x16x32_bf16 v[54:57], v[150:153], v[184:187], v[54:57]
	v_mfma_f32_16x16x32_bf16 v[50:53], v[176:179], v[184:187], v[50:53]
	v_mfma_f32_16x16x32_bf16 v[38:41], v[150:153], v[200:203], v[38:41]
	v_mfma_f32_16x16x32_bf16 v[34:37], v[176:179], v[200:203], v[34:37]
	v_mfma_f32_16x16x32_bf16 v[22:25], v[150:153], v[208:211], v[22:25]
	v_mfma_f32_16x16x32_bf16 v[18:21], v[176:179], v[208:211], v[18:21]
	v_mfma_f32_16x16x32_bf16 v[6:9], v[150:153], v[216:219], v[6:9]
	v_mfma_f32_16x16x32_bf16 v[2:5], v[176:179], v[216:219], v[2:5]
	v_mfma_f32_16x16x32_bf16 v[54:57], v[172:175], v[196:199], v[54:57]
	v_mfma_f32_16x16x32_bf16 v[50:53], v[180:183], v[196:199], v[50:53]
	v_mfma_f32_16x16x32_bf16 v[38:41], v[172:175], v[204:207], v[38:41]
	v_mfma_f32_16x16x32_bf16 v[34:37], v[180:183], v[204:207], v[34:37]
	v_mfma_f32_16x16x32_bf16 v[22:25], v[172:175], v[212:215], v[22:25]
	v_mfma_f32_16x16x32_bf16 v[18:21], v[180:183], v[212:215], v[18:21]
	v_mfma_f32_16x16x32_bf16 v[6:9], v[172:175], v[220:223], v[6:9]
	v_mfma_f32_16x16x32_bf16 v[2:5], v[180:183], v[220:223], v[2:5]
	s_barrier
	s_add_i32 s44, s44, 2
	s_add_u32 s38, s38, 0x100
	s_addc_u32 s39, s39, 0
	s_cmp_gt_u32 s44, 29
	s_cbranch_scc0 .LBB0_894
	.p2align 6

; #define PG8_STAGE(bufoff, gbase, RR, ld) do { _Pragma("unroll") for (int _i = 0; _i < 2; ++_i) \
;         __builtin_amdgcn_global_load_lds((const unsigned*)((const char*)(gbase) + (RR)[_i] * (ld) + C2[_i]), (LAS unsigned*)(lds + (bufoff) + ldsw + _i * 8192), 16, 0, 0); } while (0)
; #define PG8_LDA(dst, b, h) do { _Pragma("unroll") for (int m = 0; m < 4; ++m) _Pragma("unroll") for (int k = 0; k < 2; ++k) dst[m][k] = *(const LAS bf16x8*)(lds + PG8_SA(b, h) + aoff + m * 2048 + k * 1024); } while (0)
; #define PG8_LDB(dst, b, h) do { _Pragma("unroll") for (int n = 0; n < 2; ++n) _Pragma("unroll") for (int k = 0; k < 2; ++k) dst[n][k] = *(const LAS bf16x8*)(lds + PG8_SB(b, h) + boff + n * 2048 + k * 1024); } while (0)
; #define PG8_MMA(ai, bj, At, Bt) do { __builtin_amdgcn_s_setprio(1); _Pragma("unroll") for (int m = 0; m < 4; ++m) _Pragma("unroll") for (int n = 0; n < 2; ++n) _Pragma("unroll") for (int k = 0; k < 2; ++k) \
;         acc[ai][bj][m][n] = __builtin_amdgcn_mfma_f32_16x16x32_bf16(Bt[n][k], At[m][k], acc[ai][bj][m][n], 0, 0, 0); __builtin_amdgcn_s_setprio(0); } while (0)
; #define PG8_WAIT_V(n) asm volatile("s_waitcnt vmcnt(" #n ")" ::: "memory")
; #define PG8_WAIT_L(n) asm volatile("s_waitcnt lgkmcnt(" #n ")" ::: "memory")
; template <class Sched, class Epi>
; __device__ __forceinline__ void gemm_run(LAS unsigned char* lds, const Sched& S, const Epi& E) {
;     ...
;         for (int t = 0; t < nt; t += 2) {
;             const bool last = (t == nt - 2);
;             const char* a1 = cA + (size_t)(t + 1) * kstep;
;             const char* a2 = last ? nA : cA + (size_t)(t + 2) * kstep; const char* b2 = last ? nB : cB + (size_t)(t + 2) * kstep;
;             const unsigned la2 = last ? nlda : lda, lb2 = last ? nldb : ldb;
;             const char* a3 = a2 + kstep; const char* b3 = b2 + kstep;
;             PG8_LDB(B0, 0, 0); PG8_LDB(B1, 0, 1); PG8_SCHED; PG8_LDA(At, 0, 0); PG8_STAGE(PG8_SA(1, 1), a1 + (size_t)HALF * lda, RA, lda);
;             PG8_WAIT_V(8); PG8_WAIT_L(0); PG8_BAR; PG8_MMA(0, 0, At, B0); PG8_MMA(0, 1, At, B1); PG8_BAR; PG8_SCHED;
;             PG8_LDA(At, 0, 1); PG8_STAGE(PG8_SB(0, 0), b2, RB, lb2); PG8_STAGE(PG8_SB(0, 1), b2 + (size_t)HALF * lb2, RB, lb2); PG8_STAGE(PG8_SA(0, 0), a2, RA, la2);
;             PG8_WAIT_V(8); PG8_WAIT_L(0); PG8_BAR; PG8_MMA(1, 0, At, B0); PG8_MMA(1, 1, At, B1); PG8_BAR; PG8_SCHED;
.LBB0_998:
	s_add_u32 s15, s30, 0x100
	s_addc_u32 s54, s31, 0
	v_lshl_add_u64 v[146:147], s[28:29], 0, v[142:143]
	v_lshl_add_u64 v[148:149], s[28:29], 0, v[144:145]
	s_mov_b32 s55, -2
	s_mov_b64 s[30:31], 0
	ds_read_b128 v[156:159], v152
	ds_read_b128 v[160:163], v152 offset:1024
	ds_read_b128 v[164:167], v152 offset:2048
	ds_read_b128 v[168:171], v152 offset:3072
	ds_read_b128 v[172:175], v153
	ds_read_b128 v[176:179], v153 offset:1024
	ds_read_b128 v[180:183], v153 offset:2048
	ds_read_b128 v[184:187], v153 offset:3072
	s_add_u32 s36, s28, s30
	s_addc_u32 s37, s29, s31
	s_add_u32 s36, s36, 0x100
	s_addc_u32 s37, s37, 0
	s_add_u32 s56, s15, s30
	s_addc_u32 s57, s54, s31
	s_cmpk_eq_i32 s30, 0xf00
	s_cselect_b32 s39, s17, s37
	s_cselect_b32 s38, s16, s36
	s_cselect_b32 s37, s21, s57
	s_cselect_b32 s36, s20, s56
	v_lshl_add_u64 v[220:221], v[146:147], 0, s[30:31]
	s_add_i32 m0, s42, 0xc000
	ds_read_b128 v[188:191], v154
	ds_read_b128 v[192:195], v154 offset:1024
	ds_read_b128 v[196:199], v154 offset:2048
	ds_read_b128 v[200:203], v154 offset:3072
	ds_read_b128 v[204:207], v154 offset:4096
	ds_read_b128 v[208:211], v154 offset:5120
	ds_read_b128 v[212:215], v154 offset:6144
	ds_read_b128 v[216:219], v154 offset:7168
	global_load_lds_dwordx4 v[220:221], off
	v_lshl_add_u64 v[220:221], v[148:149], 0, s[30:31]
	s_add_i32 m0, s42, 0xe000
	s_nop 0
	global_load_lds_dwordx4 v[220:221], off
	s_waitcnt vmcnt(8)
	s_waitcnt lgkmcnt(0)
	s_barrier
	s_waitcnt lgkmcnt(0)
	v_mfma_f32_16x16x32_bf16 v[126:129], v[156:159], v[188:191], 0
	v_mfma_f32_16x16x32_bf16 v[122:125], v[164:167], v[188:191], 0
	v_mfma_f32_16x16x32_bf16 v[110:113], v[156:159], v[196:199], 0
	v_mfma_f32_16x16x32_bf16 v[106:109], v[164:167], v[196:199], 0
	v_mfma_f32_16x16x32_bf16 v[94:97], v[156:159], v[204:207], 0
	v_mfma_f32_16x16x32_bf16 v[90:93], v[164:167], v[204:207], 0
	v_mfma_f32_16x16x32_bf16 v[78:81], v[156:159], v[212:215], 0
	v_mfma_f32_16x16x32_bf16 v[74:77], v[164:167], v[212:215], 0
	v_mfma_f32_16x16x32_bf16 v[126:129], v[160:163], v[192:195], v[126:129]
	v_mfma_f32_16x16x32_bf16 v[122:125], v[168:171], v[192:195], v[122:125]
	v_mfma_f32_16x16x32_bf16 v[110:113], v[160:163], v[200:203], v[110:113]
	v_mfma_f32_16x16x32_bf16 v[106:109], v[168:171], v[200:203], v[106:109]
	v_mfma_f32_16x16x32_bf16 v[94:97], v[160:163], v[208:211], v[94:97]
	v_mfma_f32_16x16x32_bf16 v[90:93], v[168:171], v[208:211], v[90:93]
	v_mfma_f32_16x16x32_bf16 v[78:81], v[160:163], v[216:219], v[78:81]
	v_mfma_f32_16x16x32_bf16 v[74:77], v[168:171], v[216:219], v[74:77]
	v_mfma_f32_16x16x32_bf16 v[118:121], v[172:175], v[188:191], 0
	v_mfma_f32_16x16x32_bf16 v[114:117], v[180:183], v[188:191], 0
	v_mfma_f32_16x16x32_bf16 v[102:105], v[172:175], v[196:199], 0
	v_mfma_f32_16x16x32_bf16 v[98:101], v[180:183], v[196:199], 0
	v_mfma_f32_16x16x32_bf16 v[86:89], v[172:175], v[204:207], 0
	v_mfma_f32_16x16x32_bf16 v[82:85], v[180:183], v[204:207], 0
	v_mfma_f32_16x16x32_bf16 v[70:73], v[172:175], v[212:215], 0
	v_mfma_f32_16x16x32_bf16 v[66:69], v[180:183], v[212:215], 0
	v_mfma_f32_16x16x32_bf16 v[118:121], v[176:179], v[192:195], v[118:121]
	v_mfma_f32_16x16x32_bf16 v[114:117], v[184:187], v[192:195], v[114:117]
	v_mfma_f32_16x16x32_bf16 v[102:105], v[176:179], v[200:203], v[102:105]
	v_mfma_f32_16x16x32_bf16 v[98:101], v[184:187], v[200:203], v[98:101]
	v_mfma_f32_16x16x32_bf16 v[86:89], v[176:179], v[208:211], v[86:89]
	v_mfma_f32_16x16x32_bf16 v[82:85], v[184:187], v[208:211], v[82:85]
	v_mfma_f32_16x16x32_bf16 v[70:73], v[176:179], v[216:219], v[70:73]
	v_mfma_f32_16x16x32_bf16 v[66:69], v[184:187], v[216:219], v[66:69]
	s_barrier
	v_lshl_add_u64 v[220:221], s[36:37], 0, v[132:133]
	s_add_i32 s56, s49, s3
	v_lshl_add_u64 v[220:221], v[220:221], 0, v[130:131]
	s_mov_b32 m0, s56
	ds_read_b128 v[188:191], v154 offset:16384
	ds_read_b128 v[192:195], v154 offset:17408
	ds_read_b128 v[196:199], v154 offset:18432
	ds_read_b128 v[200:203], v154 offset:19456
	ds_read_b128 v[204:207], v154 offset:20480
	ds_read_b128 v[208:211], v154 offset:21504
	ds_read_b128 v[212:215], v154 offset:22528
	ds_read_b128 v[216:219], v154 offset:23552
	global_load_lds_dwordx4 v[220:221], off
	s_add_i32 m0, s56, 0x2000
	s_add_u32 s56, s36, 0x80000
	v_lshl_add_u64 v[222:223], s[36:37], 0, v[136:137]
	s_addc_u32 s57, s37, 0
	v_lshl_add_u64 v[222:223], v[222:223], 0, v[130:131]
	v_lshl_add_u64 v[224:225], s[56:57], 0, v[132:133]
	s_add_i32 s58, s50, s3
	global_load_lds_dwordx4 v[222:223], off
	v_lshl_add_u64 v[224:225], v[224:225], 0, v[130:131]
	s_mov_b32 m0, s58
	v_lshl_add_u64 v[226:227], s[38:39], 0, v[140:141]
	global_load_lds_dwordx4 v[224:225], off
	v_lshl_add_u64 v[224:225], s[56:57], 0, v[136:137]
	v_lshl_add_u64 v[224:225], v[224:225], 0, v[130:131]
	s_add_i32 m0, s58, 0x2000
	v_lshl_add_u64 v[226:227], v[226:227], 0, v[130:131]
	global_load_lds_dwordx4 v[224:225], off
	v_lshl_add_u64 v[224:225], s[38:39], 0, v[138:139]
	v_lshl_add_u64 v[224:225], v[224:225], 0, v[130:131]
	s_mov_b32 m0, s42
	s_nop 0
	global_load_lds_dwordx4 v[224:225], off
	s_mov_b32 m0, s43
	s_nop 0
	global_load_lds_dwordx4 v[226:227], off
	s_waitcnt vmcnt(8)
	s_waitcnt lgkmcnt(0)
	s_barrier
; #define PG8_STAGE(bufoff, gbase, RR, ld) do { _Pragma("unroll") for (int _i = 0; _i < 2; ++_i) \
;         __builtin_amdgcn_global_load_lds((const unsigned*)((const char*)(gbase) + (RR)[_i] * (ld) + C2[_i]), (LAS unsigned*)(lds + (bufoff) + ldsw + _i * 8192), 16, 0, 0); } while (0)
; #define PG8_LDA(dst, b, h) do { _Pragma("unroll") for (int m = 0; m < 4; ++m) _Pragma("unroll") for (int k = 0; k < 2; ++k) dst[m][k] = *(const LAS bf16x8*)(lds + PG8_SA(b, h) + aoff + m * 2048 + k * 1024); } while (0)
; #define PG8_LDB(dst, b, h) do { _Pragma("unroll") for (int n = 0; n < 2; ++n) _Pragma("unroll") for (int k = 0; k < 2; ++k) dst[n][k] = *(const LAS bf16x8*)(lds + PG8_SB(b, h) + boff + n * 2048 + k * 1024); } while (0)
; #define PG8_MMA(ai, bj, At, Bt) do { __builtin_amdgcn_s_setprio(1); _Pragma("unroll") for (int m = 0; m < 4; ++m) _Pragma("unroll") for (int n = 0; n < 2; ++n) _Pragma("unroll") for (int k = 0; k < 2; ++k) \
;         acc[ai][bj][m][n] = __builtin_amdgcn_mfma_f32_16x16x32_bf16(Bt[n][k], At[m][k], acc[ai][bj][m][n], 0, 0, 0); __builtin_amdgcn_s_setprio(0); } while (0)
; #define PG8_WAIT_V(n) asm volatile("s_waitcnt vmcnt(" #n ")" ::: "memory")
; #define PG8_WAIT_L(n) asm volatile("s_waitcnt lgkmcnt(" #n ")" ::: "memory")
; #define PG8_BAR __builtin_amdgcn_s_barrier()
; #define PG8_SCHED __builtin_amdgcn_sched_barrier(0)
; template <class Sched, class Epi>
; __device__ __forceinline__ void gemm_run(LAS unsigned char* lds, const Sched& S, const Epi& E) {
;     ...
;             PG8_WAIT_V(8); PG8_WAIT_L(0); PG8_BAR; PG8_MMA(1, 0, At, B0); PG8_MMA(1, 1, At, B1); PG8_BAR; PG8_SCHED;
;             PG8_LDB(B0, 1, 0); PG8_LDB(B1, 1, 1); PG8_SCHED; PG8_LDA(At, 1, 0); PG8_STAGE(PG8_SA(0, 1), a2 + (size_t)HALF * la2, RA, la2);
;             PG8_WAIT_V(8); PG8_WAIT_L(0); PG8_BAR; PG8_MMA(0, 0, At, B0); PG8_MMA(0, 1, At, B1); PG8_BAR; PG8_SCHED;
	s_waitcnt lgkmcnt(0)
	v_mfma_f32_16x16x32_bf16 v[62:65], v[156:159], v[188:191], 0
	v_mfma_f32_16x16x32_bf16 v[58:61], v[164:167], v[188:191], 0
	v_mfma_f32_16x16x32_bf16 v[46:49], v[156:159], v[196:199], 0
	v_mfma_f32_16x16x32_bf16 v[42:45], v[164:167], v[196:199], 0
	v_mfma_f32_16x16x32_bf16 v[30:33], v[156:159], v[204:207], 0
	v_mfma_f32_16x16x32_bf16 v[26:29], v[164:167], v[204:207], 0
	v_mfma_f32_16x16x32_bf16 v[14:17], v[156:159], v[212:215], 0
	v_mfma_f32_16x16x32_bf16 v[10:13], v[164:167], v[212:215], 0
	v_mfma_f32_16x16x32_bf16 v[62:65], v[160:163], v[192:195], v[62:65]
	v_mfma_f32_16x16x32_bf16 v[58:61], v[168:171], v[192:195], v[58:61]
	v_mfma_f32_16x16x32_bf16 v[46:49], v[160:163], v[200:203], v[46:49]
	v_mfma_f32_16x16x32_bf16 v[42:45], v[168:171], v[200:203], v[42:45]
	v_mfma_f32_16x16x32_bf16 v[30:33], v[160:163], v[208:211], v[30:33]
	v_mfma_f32_16x16x32_bf16 v[26:29], v[168:171], v[208:211], v[26:29]
	v_mfma_f32_16x16x32_bf16 v[14:17], v[160:163], v[216:219], v[14:17]
	v_mfma_f32_16x16x32_bf16 v[10:13], v[168:171], v[216:219], v[10:13]
	v_mfma_f32_16x16x32_bf16 v[54:57], v[172:175], v[188:191], 0
	v_mfma_f32_16x16x32_bf16 v[50:53], v[180:183], v[188:191], 0
	v_mfma_f32_16x16x32_bf16 v[38:41], v[172:175], v[196:199], 0
	v_mfma_f32_16x16x32_bf16 v[34:37], v[180:183], v[196:199], 0
	v_mfma_f32_16x16x32_bf16 v[22:25], v[172:175], v[204:207], 0
	v_mfma_f32_16x16x32_bf16 v[18:21], v[180:183], v[204:207], 0
	v_mfma_f32_16x16x32_bf16 v[6:9], v[172:175], v[212:215], 0
	v_mfma_f32_16x16x32_bf16 v[2:5], v[180:183], v[212:215], 0
	v_mfma_f32_16x16x32_bf16 v[54:57], v[176:179], v[192:195], v[54:57]
	v_mfma_f32_16x16x32_bf16 v[50:53], v[184:187], v[192:195], v[50:53]
	v_mfma_f32_16x16x32_bf16 v[38:41], v[176:179], v[200:203], v[38:41]
	v_mfma_f32_16x16x32_bf16 v[34:37], v[184:187], v[200:203], v[34:37]
	v_mfma_f32_16x16x32_bf16 v[22:25], v[176:179], v[208:211], v[22:25]
	v_mfma_f32_16x16x32_bf16 v[18:21], v[184:187], v[208:211], v[18:21]
	v_mfma_f32_16x16x32_bf16 v[6:9], v[176:179], v[216:219], v[6:9]
	v_mfma_f32_16x16x32_bf16 v[2:5], v[184:187], v[216:219], v[2:5]
	s_barrier
	s_add_i32 s56, 0, 0x18000
	s_add_i32 s57, 0, 0x1c000
	v_add_u32_e32 v168, s56, v151
	v_add_u32_e32 v184, s57, v151
	ds_read_b128 v[156:159], v168
	ds_read_b128 v[160:163], v168 offset:1024
	ds_read_b128 v[164:167], v168 offset:2048
	ds_read_b128 v[168:171], v168 offset:3072
	ds_read_b128 v[172:175], v184
	ds_read_b128 v[176:179], v184 offset:1024
	ds_read_b128 v[180:183], v184 offset:2048
	ds_read_b128 v[184:187], v184 offset:3072
	s_add_u32 s38, s38, 0x80000
	s_addc_u32 s39, s39, 0
	v_lshl_add_u64 v[228:229], s[38:39], 0, v[138:139]
	s_mov_b32 m0, s44
	v_lshl_add_u64 v[228:229], v[228:229], 0, v[130:131]
	ds_read_b128 v[188:191], v154 offset:32768
	ds_read_b128 v[192:195], v154 offset:33792
	ds_read_b128 v[196:199], v154 offset:34816
	ds_read_b128 v[200:203], v154 offset:35840
	ds_read_b128 v[204:207], v154 offset:36864
	ds_read_b128 v[208:211], v154 offset:37888
	ds_read_b128 v[212:215], v154 offset:38912
	ds_read_b128 v[216:219], v154 offset:39936
	global_load_lds_dwordx4 v[228:229], off
	v_lshl_add_u64 v[228:229], s[38:39], 0, v[140:141]
	v_lshl_add_u64 v[228:229], v[228:229], 0, v[130:131]
	s_mov_b32 m0, s45
	s_nop 0
	global_load_lds_dwordx4 v[228:229], off
	s_waitcnt vmcnt(8)
	s_waitcnt lgkmcnt(0)
	s_barrier
	s_waitcnt lgkmcnt(0)
	v_mfma_f32_16x16x32_bf16 v[126:129], v[156:159], v[188:191], v[126:129]
	v_mfma_f32_16x16x32_bf16 v[122:125], v[164:167], v[188:191], v[122:125]
	v_mfma_f32_16x16x32_bf16 v[110:113], v[156:159], v[196:199], v[110:113]
	v_mfma_f32_16x16x32_bf16 v[106:109], v[164:167], v[196:199], v[106:109]
	v_mfma_f32_16x16x32_bf16 v[94:97], v[156:159], v[204:207], v[94:97]
	v_mfma_f32_16x16x32_bf16 v[90:93], v[164:167], v[204:207], v[90:93]
	v_mfma_f32_16x16x32_bf16 v[78:81], v[156:159], v[212:215], v[78:81]
	v_mfma_f32_16x16x32_bf16 v[74:77], v[164:167], v[212:215], v[74:77]
	v_mfma_f32_16x16x32_bf16 v[126:129], v[160:163], v[192:195], v[126:129]
	v_mfma_f32_16x16x32_bf16 v[122:125], v[168:171], v[192:195], v[122:125]
	v_mfma_f32_16x16x32_bf16 v[110:113], v[160:163], v[200:203], v[110:113]
	v_mfma_f32_16x16x32_bf16 v[106:109], v[168:171], v[200:203], v[106:109]
	v_mfma_f32_16x16x32_bf16 v[94:97], v[160:163], v[208:211], v[94:97]
	v_mfma_f32_16x16x32_bf16 v[90:93], v[168:171], v[208:211], v[90:93]
	v_mfma_f32_16x16x32_bf16 v[78:81], v[160:163], v[216:219], v[78:81]
	v_mfma_f32_16x16x32_bf16 v[74:77], v[168:171], v[216:219], v[74:77]
	v_mfma_f32_16x16x32_bf16 v[118:121], v[172:175], v[188:191], v[118:121]
	v_mfma_f32_16x16x32_bf16 v[114:117], v[180:183], v[188:191], v[114:117]
	v_mfma_f32_16x16x32_bf16 v[102:105], v[172:175], v[196:199], v[102:105]
	v_mfma_f32_16x16x32_bf16 v[98:101], v[180:183], v[196:199], v[98:101]
	v_mfma_f32_16x16x32_bf16 v[86:89], v[172:175], v[204:207], v[86:89]
	v_mfma_f32_16x16x32_bf16 v[82:85], v[180:183], v[204:207], v[82:85]
	v_mfma_f32_16x16x32_bf16 v[70:73], v[172:175], v[212:215], v[70:73]
	v_mfma_f32_16x16x32_bf16 v[66:69], v[180:183], v[212:215], v[66:69]
	v_mfma_f32_16x16x32_bf16 v[118:121], v[176:179], v[192:195], v[118:121]
	v_mfma_f32_16x16x32_bf16 v[114:117], v[184:187], v[192:195], v[114:117]
	v_mfma_f32_16x16x32_bf16 v[102:105], v[176:179], v[200:203], v[102:105]
	v_mfma_f32_16x16x32_bf16 v[98:101], v[184:187], v[200:203], v[98:101]
	v_mfma_f32_16x16x32_bf16 v[86:89], v[176:179], v[208:211], v[86:89]
	v_mfma_f32_16x16x32_bf16 v[82:85], v[184:187], v[208:211], v[82:85]
	v_mfma_f32_16x16x32_bf16 v[70:73], v[176:179], v[216:219], v[70:73]
	v_mfma_f32_16x16x32_bf16 v[66:69], v[184:187], v[216:219], v[66:69]
	s_barrier
; #define PG8_STAGE(bufoff, gbase, RR, ld) do { _Pragma("unroll") for (int _i = 0; _i < 2; ++_i) \
;         __builtin_amdgcn_global_load_lds((const unsigned*)((const char*)(gbase) + (RR)[_i] * (ld) + C2[_i]), (LAS unsigned*)(lds + (bufoff) + ldsw + _i * 8192), 16, 0, 0); } while (0)
; #define PG8_LDA(dst, b, h) do { _Pragma("unroll") for (int m = 0; m < 4; ++m) _Pragma("unroll") for (int k = 0; k < 2; ++k) dst[m][k] = *(const LAS bf16x8*)(lds + PG8_SA(b, h) + aoff + m * 2048 + k * 1024); } while (0)
; #define PG8_MMA(ai, bj, At, Bt) do { __builtin_amdgcn_s_setprio(1); _Pragma("unroll") for (int m = 0; m < 4; ++m) _Pragma("unroll") for (int n = 0; n < 2; ++n) _Pragma("unroll") for (int k = 0; k < 2; ++k) \
;         acc[ai][bj][m][n] = __builtin_amdgcn_mfma_f32_16x16x32_bf16(Bt[n][k], At[m][k], acc[ai][bj][m][n], 0, 0, 0); __builtin_amdgcn_s_setprio(0); } while (0)
; #define PG8_WAIT_V(n) asm volatile("s_waitcnt vmcnt(" #n ")" ::: "memory")
; #define PG8_WAIT_L(n) asm volatile("s_waitcnt lgkmcnt(" #n ")" ::: "memory")
; #define PG8_BAR __builtin_amdgcn_s_barrier()
; #define PG8_SCHED __builtin_amdgcn_sched_barrier(0)
; template <class Sched, class Epi>
; __device__ __forceinline__ void gemm_run(LAS unsigned char* lds, const Sched& S, const Epi& E) {
;     ...
;             PG8_LDA(At, 1, 1); PG8_STAGE(PG8_SB(1, 0), b3, RB, lb2); PG8_STAGE(PG8_SB(1, 1), b3 + (size_t)HALF * lb2, RB, lb2); PG8_STAGE(PG8_SA(1, 0), a3, RA, la2);
;             PG8_WAIT_V(8); PG8_WAIT_L(0); PG8_BAR; PG8_MMA(1, 0, At, B0); PG8_MMA(1, 1, At, B1); PG8_BAR; PG8_SCHED;
;         }
	s_add_i32 s38, s56, s3
	v_lshl_add_u64 v[220:221], v[220:221], 0, s[6:7]
	s_mov_b32 m0, s38
	ds_read_b128 v[188:191], v154 offset:49152
	ds_read_b128 v[192:195], v154 offset:50176
	ds_read_b128 v[196:199], v154 offset:51200
	ds_read_b128 v[200:203], v154 offset:52224
	ds_read_b128 v[204:207], v154 offset:53248
	ds_read_b128 v[208:211], v154 offset:54272
	ds_read_b128 v[212:215], v154 offset:55296
	ds_read_b128 v[216:219], v154 offset:56320
	global_load_lds_dwordx4 v[220:221], off
	s_add_i32 m0, s38, 0x2000
	s_add_u32 s36, s36, 0x80080
	v_lshl_add_u64 v[220:221], v[222:223], 0, s[6:7]
	s_addc_u32 s37, s37, 0
	global_load_lds_dwordx4 v[220:221], off
	v_lshl_add_u64 v[220:221], s[36:37], 0, v[132:133]
	s_add_i32 s38, s57, s3
	v_lshl_add_u64 v[220:221], v[220:221], 0, v[130:131]
	s_mov_b32 m0, s38
	s_nop 0
	global_load_lds_dwordx4 v[220:221], off
	v_lshl_add_u64 v[220:221], s[36:37], 0, v[136:137]
	v_lshl_add_u64 v[220:221], v[220:221], 0, v[130:131]
	s_add_i32 m0, s38, 0x2000
	s_nop 0
	global_load_lds_dwordx4 v[220:221], off
	v_lshl_add_u64 v[220:221], v[224:225], 0, s[6:7]
	s_mov_b32 m0, s47
	s_nop 0
	global_load_lds_dwordx4 v[220:221], off
	v_lshl_add_u64 v[220:221], v[226:227], 0, s[6:7]
	s_mov_b32 m0, s48
	s_nop 0
	global_load_lds_dwordx4 v[220:221], off
	s_waitcnt vmcnt(8)
	s_waitcnt lgkmcnt(0)
	s_barrier
	s_waitcnt lgkmcnt(0)
	v_mfma_f32_16x16x32_bf16 v[62:65], v[156:159], v[188:191], v[62:65]
	v_mfma_f32_16x16x32_bf16 v[58:61], v[164:167], v[188:191], v[58:61]
	v_mfma_f32_16x16x32_bf16 v[46:49], v[156:159], v[196:199], v[46:49]
	v_mfma_f32_16x16x32_bf16 v[42:45], v[164:167], v[196:199], v[42:45]
	v_mfma_f32_16x16x32_bf16 v[30:33], v[156:159], v[204:207], v[30:33]
	v_mfma_f32_16x16x32_bf16 v[26:29], v[164:167], v[204:207], v[26:29]
	v_mfma_f32_16x16x32_bf16 v[14:17], v[156:159], v[212:215], v[14:17]
	v_mfma_f32_16x16x32_bf16 v[10:13], v[164:167], v[212:215], v[10:13]
	v_mfma_f32_16x16x32_bf16 v[62:65], v[160:163], v[192:195], v[62:65]
	v_mfma_f32_16x16x32_bf16 v[58:61], v[168:171], v[192:195], v[58:61]
	v_mfma_f32_16x16x32_bf16 v[46:49], v[160:163], v[200:203], v[46:49]
	v_mfma_f32_16x16x32_bf16 v[42:45], v[168:171], v[200:203], v[42:45]
	v_mfma_f32_16x16x32_bf16 v[30:33], v[160:163], v[208:211], v[30:33]
	v_mfma_f32_16x16x32_bf16 v[26:29], v[168:171], v[208:211], v[26:29]
	v_mfma_f32_16x16x32_bf16 v[14:17], v[160:163], v[216:219], v[14:17]
	v_mfma_f32_16x16x32_bf16 v[10:13], v[168:171], v[216:219], v[10:13]
	v_mfma_f32_16x16x32_bf16 v[54:57], v[172:175], v[188:191], v[54:57]
	v_mfma_f32_16x16x32_bf16 v[50:53], v[180:183], v[188:191], v[50:53]
	v_mfma_f32_16x16x32_bf16 v[38:41], v[172:175], v[196:199], v[38:41]
	v_mfma_f32_16x16x32_bf16 v[34:37], v[180:183], v[196:199], v[34:37]
	v_mfma_f32_16x16x32_bf16 v[22:25], v[172:175], v[204:207], v[22:25]
	v_mfma_f32_16x16x32_bf16 v[18:21], v[180:183], v[204:207], v[18:21]
	v_mfma_f32_16x16x32_bf16 v[6:9], v[172:175], v[212:215], v[6:9]
	v_mfma_f32_16x16x32_bf16 v[2:5], v[180:183], v[212:215], v[2:5]
	v_mfma_f32_16x16x32_bf16 v[54:57], v[176:179], v[192:195], v[54:57]
	v_mfma_f32_16x16x32_bf16 v[50:53], v[184:187], v[192:195], v[50:53]
	v_mfma_f32_16x16x32_bf16 v[38:41], v[176:179], v[200:203], v[38:41]
	v_mfma_f32_16x16x32_bf16 v[34:37], v[184:187], v[200:203], v[34:37]
	v_mfma_f32_16x16x32_bf16 v[22:25], v[176:179], v[208:211], v[22:25]
	v_mfma_f32_16x16x32_bf16 v[18:21], v[184:187], v[208:211], v[18:21]
	v_mfma_f32_16x16x32_bf16 v[6:9], v[176:179], v[216:219], v[6:9]
	v_mfma_f32_16x16x32_bf16 v[2:5], v[184:187], v[216:219], v[2:5]
	s_barrier
	s_add_i32 s55, s55, 2
	s_add_u32 s30, s30, 0x100
	s_addc_u32 s31, s31, 0
	s_cmp_gt_u32 s55, 29
	s_cbranch_scc0 .LBB0_999
	.p2align 6
